# attention loops: mask-free path for key tiles 1-3 on waves that do not touch a sequence end (window mask provably true there); on top of wait fix, XCD-local unit order, loosened GEMM waits
# speedup vs baseline: 1.0072x; 1.0072x over previous
; __device__ __forceinline__ float attn_tile_exp(f32x16& st, int j, float tlf, float bsl, float rlo, float rhi) {
;     float sum = 0.f;
; #pragma unroll
;     for (int i = 0; i < 16; ++i) { const float tmp = (float)(32 * j - 64 + (i & 3) + 8 * (i >> 2)) + tlf;
;         float arg = __builtin_fmaf(-bsl, __builtin_fabsf(tmp), st[i]);
; template <bool FUSED> __device__ __forceinline__ void attn_phase(const Args& a, LAS unsigned char* lds, int tid, int lane, int wave) {
;     ...
;         const float bsl = __builtin_amdgcn_exp2f(-(float)(slot + 1)) * (float)w.dil * LOG2E;
;         int tl = 4 * h - l31; asm volatile("" : "+v"(tl));
;         const float tlf = (float)tl;
;         const int lo_i = -iq > -64 ? -iq : -64, hi_i = (L - 1 - iq) < 64 ? (L - 1 - iq) : 64;
;         const float rlo = (float)lo_i, rhi = (float)hi_i;
;         const int wq0 = i0 + 32 * wave;
;         const bool edge = (wq0 < 64) || (wq0 + 32 > L - 64);
;         float sum = 0.f;
;         f32x16 o[2]; o[0] = f32x16{}; o[1] = f32x16{};
; #pragma unroll
;         for (int j = 0; j < 5; ++j) {
;             f32x16 st;
; #pragma unroll
;             for (int i = 0; i < 16; ++i) st[i] = -mb;
;             LAS const unsigned char* kp = lds + (32 * wave + 32 * j + l31) * KP + 16 * h;
; #pragma unroll
;             for (int ks = 0; ks < 4; ++ks) { const bf16x8 kf = *(LAS const bf16x8*)(kp + 32 * ks); st = __builtin_amdgcn_mfma_f32_32x32x16_bf16(kf, qf[ks], st, 0, 0, 0); }
;             sum += attn_tile_exp(st, j, tlf, bsl, rlo, rhi);
; #pragma unroll
;             for (int s2 = 0; s2 < 2; ++s2) { u32x4 pw; pw.x = pk2(st[8 * s2 + 0], st[8 * s2 + 1]); pw.y = pk2(st[8 * s2 + 2], st[8 * s2 + 3]); pw.z = pk2(st[8 * s2 + 4], st[8 * s2 + 5]); pw.w = pk2(st[8 * s2 + 6], st[8 * s2 + 7]);
;                 const bf16x8 pf = __builtin_bit_cast(bf16x8, pw);
;                 LAS const unsigned char* vp = lds + LDS_VOFF + (32 * wave + 32 * j + 16 * s2 + 4 * h + q) * VP + 32 * blk + 8 * p;
; #pragma unroll
;                 for (int dt = 0; dt < 2; ++dt) { const s16x4 lo = trrd(vp + dt * 64), hi = trrd(vp + 8 * VP + dt * 64);
;                     const bf16x8 vf = __builtin_shufflevector(lo, hi, 0, 1, 2, 3, 4, 5, 6, 7);
;                     o[dt] = __builtin_amdgcn_mfma_f32_32x32x16_bf16(vf, pf, o[dt], 0, 0, 0); } }
;             __builtin_amdgcn_sched_barrier(0);
;         }
.Lattn1_join:
	v_xor_b32_e32 v0, 0x80000000, v222
	v_mov_b32_e32 v1, v0
	v_mov_b32_e32 v2, v0
	v_mov_b32_e32 v3, v0
	v_mov_b32_e32 v4, v0
	v_mov_b32_e32 v5, v0
	v_mov_b32_e32 v6, v0
	v_mov_b32_e32 v7, v0
	v_mov_b32_e32 v8, v0
	v_mov_b32_e32 v9, v0
	v_mov_b32_e32 v10, v0
	v_mov_b32_e32 v11, v0
	v_mov_b32_e32 v12, v0
	v_mov_b32_e32 v13, v0
	v_mov_b32_e32 v14, v0
	v_mov_b32_e32 v15, v0
	v_exp_f32_e64 v46, -v32
	v_pk_mul_f32 v[32:33], v[58:59], v[36:37] op_sel_hi:[0,1]
	s_waitcnt lgkmcnt(0)
	v_mfma_f32_32x32x16_bf16 v[16:31], v[38:41], v[136:139], v[0:15]
	ds_read_b128 v[38:41], v199 offset:64
	v_mul_f32_e64 v32, v32, v34
	v_mul_f32_e64 v33, v33, v35
	s_and_b32 s77, s67, 31
	v_cvt_pk_bf16_f32 v143, v32, v33
	ds_read_b128 v[32:35], v199 offset:96
	s_add_i32 s6, s6, -1
	s_and_b32 s6, s6, s77
	v_mfma_f32_32x32x16_bf16 v[16:31], v[42:45], v[132:135], v[16:31]
	s_lshr_b32 s76, 0x2000, s75
	v_lshl_add_u32 v168, s6, 8, v145
	s_lshl_b32 s6, 1, s75
	v_sub_u32_e32 v37, 0, v168
	v_cvt_f32_u32_e32 v42, s6
	v_cvt_f32_i32_e32 v225, v48
	v_max_i32_e32 v37, 0xffffffc0, v37
	s_waitcnt lgkmcnt(1)
	v_mfma_f32_32x32x16_bf16 v[16:31], v[38:41], v[128:131], v[16:31]
	v_xad_u32 v38, v168, -1, s76
	v_min_i32_e32 v38, 64, v38
	v_cvt_f32_i32_e32 v169, v37
	v_cvt_f32_i32_e32 v223, v38
	v_mul_f32_e32 v36, v46, v42
	v_mul_f32_e32 v224, 0xbfb8aa3b, v36
	s_waitcnt lgkmcnt(0)
	v_mfma_f32_32x32x16_bf16 v[16:31], v[32:35], v[140:143], v[16:31]
	v_add_f32_e32 v32, 0xc2800000, v225
	v_cmp_nge_f32_e32 vcc, v32, v169
	v_cmp_nle_f32_e64 s[6:7], v32, v223
	s_or_b64 vcc, vcc, s[6:7]
	v_add_f32_e32 v33, 0xc27c0000, v225
	v_cmp_nle_f32_e64 s[6:7], v33, v223
	s_nop 5
	v_fma_f32 v16, v224, |v32|, v16
	v_cndmask_b32_e32 v16, v16, v221, vcc
	v_cmp_nge_f32_e32 vcc, v33, v169
	v_fma_f32 v17, v224, |v33|, v17
	s_or_b64 vcc, vcc, s[6:7]
	v_cndmask_b32_e32 v17, v17, v221, vcc
	v_exp_f32_e32 v33, v17
	v_add_f32_e32 v17, 0xc2780000, v225
	v_cmp_nge_f32_e32 vcc, v17, v169
	v_cmp_nle_f32_e64 s[6:7], v17, v223
	v_fma_f32 v18, v224, |v17|, v18
	s_or_b64 vcc, vcc, s[6:7]
	v_cndmask_b32_e32 v17, v18, v221, vcc
	v_exp_f32_e32 v34, v17
	v_add_f32_e32 v17, 0xc2740000, v225
	v_cmp_nge_f32_e32 vcc, v17, v169
	v_cmp_nle_f32_e64 s[6:7], v17, v223
	v_fma_f32 v18, v224, |v17|, v19
	s_or_b64 vcc, vcc, s[6:7]
	v_cndmask_b32_e32 v17, v18, v221, vcc
	v_exp_f32_e32 v35, v17
	v_add_f32_e32 v17, 0xc2600000, v225
	v_cmp_nge_f32_e32 vcc, v17, v169
	v_cmp_nle_f32_e64 s[6:7], v17, v223
	v_fma_f32 v18, v224, |v17|, v20
	s_or_b64 vcc, vcc, s[6:7]
	v_cndmask_b32_e32 v17, v18, v221, vcc
	v_exp_f32_e32 v36, v17
	v_add_f32_e32 v17, 0xc25c0000, v225
	v_cmp_nge_f32_e32 vcc, v17, v169
	v_cmp_nle_f32_e64 s[6:7], v17, v223
	v_fma_f32 v18, v224, |v17|, v21
	s_or_b64 vcc, vcc, s[6:7]
	v_cndmask_b32_e32 v17, v18, v221, vcc
	v_exp_f32_e32 v37, v17
	v_add_f32_e32 v17, 0xc2580000, v225
	v_cmp_nge_f32_e32 vcc, v17, v169
	v_cmp_nle_f32_e64 s[6:7], v17, v223
	v_fma_f32 v18, v224, |v17|, v22
	s_or_b64 vcc, vcc, s[6:7]
	v_cndmask_b32_e32 v17, v18, v221, vcc
	v_exp_f32_e32 v32, v16
	v_exp_f32_e32 v38, v17
	v_add_f32_e32 v17, 0xc2540000, v225
	v_cmp_nge_f32_e32 vcc, v17, v169
	v_cmp_nle_f32_e64 s[6:7], v17, v223
	v_fma_f32 v18, v224, |v17|, v23
	s_or_b64 vcc, vcc, s[6:7]
	v_cndmask_b32_e32 v17, v18, v221, vcc
	v_add_f32_e32 v16, 0, v32
	v_exp_f32_e32 v23, v17
	v_add_f32_e32 v17, 0xc2400000, v225
	v_add_f32_e32 v16, v33, v16
	v_cmp_nge_f32_e32 vcc, v17, v169
	v_cmp_nle_f32_e64 s[6:7], v17, v223
	v_add_f32_e32 v16, v34, v16
	v_fma_f32 v18, v224, |v17|, v24
	s_or_b64 vcc, vcc, s[6:7]
	v_add_f32_e32 v16, v35, v16
	v_cndmask_b32_e32 v17, v18, v221, vcc
	v_add_f32_e32 v16, v36, v16
	v_exp_f32_e32 v52, v17
	v_add_f32_e32 v16, v37, v16
	v_add_f32_e32 v16, v38, v16
	v_add_f32_e32 v16, v23, v16
	v_add_f32_e32 v60, v52, v16
	v_add_f32_e32 v16, 0xc23c0000, v225
	v_cmp_nge_f32_e32 vcc, v16, v169
	v_cmp_nle_f32_e64 s[6:7], v16, v223
	v_fma_f32 v17, v224, |v16|, v25
	s_or_b64 vcc, vcc, s[6:7]
	v_cndmask_b32_e32 v16, v17, v221, vcc
	v_exp_f32_e32 v61, v16
	v_add_f32_e32 v16, 0xc2380000, v225
	v_cmp_nge_f32_e32 vcc, v16, v169
	v_cmp_nle_f32_e64 s[6:7], v16, v223
	v_fma_f32 v17, v224, |v16|, v26
	s_or_b64 vcc, vcc, s[6:7]
	v_cndmask_b32_e32 v16, v17, v221, vcc
	v_exp_f32_e32 v62, v16
	v_add_f32_e32 v16, 0xc2340000, v225
	v_cmp_nge_f32_e32 vcc, v16, v169
	v_cmp_nle_f32_e64 s[6:7], v16, v223
	v_fma_f32 v17, v224, |v16|, v27
	s_or_b64 vcc, vcc, s[6:7]
	v_cndmask_b32_e32 v16, v17, v221, vcc
	v_exp_f32_e32 v63, v16
	v_add_f32_e32 v16, 0xc2200000, v225
	v_cmp_nge_f32_e32 vcc, v16, v169
	v_cmp_nle_f32_e64 s[6:7], v16, v223
	v_fma_f32 v17, v224, |v16|, v28
	s_or_b64 vcc, vcc, s[6:7]
	v_cndmask_b32_e32 v16, v17, v221, vcc
	v_exp_f32_e32 v226, v16
	v_add_f32_e32 v16, 0xc21c0000, v225
	v_cmp_nge_f32_e32 vcc, v16, v169
	v_cmp_nle_f32_e64 s[6:7], v16, v223
	v_fma_f32 v17, v224, |v16|, v29
	s_or_b64 vcc, vcc, s[6:7]
	v_cndmask_b32_e32 v16, v17, v221, vcc
	v_exp_f32_e32 v227, v16
	v_add_f32_e32 v16, 0xc2180000, v225
	v_cmp_nge_f32_e32 vcc, v16, v169
	v_cmp_nle_f32_e64 s[6:7], v16, v223
	v_fma_f32 v17, v224, |v16|, v30
	s_or_b64 vcc, vcc, s[6:7]
	v_cndmask_b32_e32 v20, v17, v221, vcc
	ds_read_b64_tr_b16 v[16:17], v200 offset:55296
	ds_read_b64_tr_b16 v[18:19], v200 offset:56832
	ds_read_b64_tr_b16 v[26:27], v200 offset:56896
	ds_read_b64_tr_b16 v[24:25], v200 offset:55360
	v_add_f32_e32 v28, 0xc2140000, v225
	v_exp_f32_e32 v228, v20
	v_cvt_pk_bf16_f32 v20, v32, v33
	v_cvt_pk_bf16_f32 v21, v34, v35
	v_cvt_pk_bf16_f32 v22, v36, v37
	v_cvt_pk_bf16_f32 v23, v38, v23
	v_cmp_nge_f32_e32 vcc, v28, v169
	v_cmp_nle_f32_e64 s[6:7], v28, v223
	s_waitcnt lgkmcnt(2)
	v_mfma_f32_32x32x16_bf16 v[32:47], v[16:19], v[20:23], 0
	v_fma_f32 v16, v224, |v28|, v31
	s_or_b64 vcc, vcc, s[6:7]
	v_cndmask_b32_e32 v53, v16, v221, vcc
	ds_read_b64_tr_b16 v[48:49], v200 offset:58368
	ds_read_b64_tr_b16 v[50:51], v200 offset:59904
	v_exp_f32_e32 v229, v53
	ds_read_b64_tr_b16 v[58:59], v200 offset:59968
	ds_read_b64_tr_b16 v[56:57], v200 offset:58432
	v_cvt_pk_bf16_f32 v52, v52, v61
	s_waitcnt lgkmcnt(4)
	v_mfma_f32_32x32x16_bf16 v[16:31], v[24:27], v[20:23], 0
	v_cvt_pk_bf16_f32 v53, v62, v63
	v_cvt_pk_bf16_f32 v54, v226, v227
	v_cvt_pk_bf16_f32 v55, v228, v229
	s_waitcnt lgkmcnt(2)
	s_nop 0
	v_mfma_f32_32x32x16_bf16 v[32:47], v[48:51], v[52:55], v[32:47]
	v_add_f32_e32 v48, v61, v60
	v_add_f32_e32 v48, v62, v48
	v_add_f32_e32 v48, v63, v48
	v_add_f32_e32 v48, v226, v48
	v_add_f32_e32 v48, v227, v48
	v_add_f32_e32 v48, v228, v48
	v_add_f32_e32 v48, v229, v48
	s_waitcnt lgkmcnt(0)
	v_mfma_f32_32x32x16_bf16 v[16:31], v[56:59], v[52:55], v[16:31]
	v_add_f32_e32 v238, 0, v48
	v_cmp_neq_f32_e32 vcc, 0xc2800000, v169
	s_mov_b64 s[6:7], vcc
	v_cmp_neq_f32_e32 vcc, 0x42800000, v223
	s_or_b64 vcc, vcc, s[6:7]
	s_cbranch_vccnz .Lattn1_slow
; #define LAS __attribute__((address_space(3)))
; __device__ __forceinline__ unsigned pk2(float lo, float hi) { f32x2_t v = {lo, hi}; bf16x2_t b = __builtin_convertvector(v, bf16x2_t); return __builtin_bit_cast(unsigned, b); }
; __device__ __forceinline__ s16x4 trrd(LAS const unsigned char* p) { return __builtin_bit_cast(s16x4, __builtin_amdgcn_ds_read_tr16_b64_v4i16((LAS v4i16_t*)p)); }
; __device__ __forceinline__ float attn_tile_exp(f32x16& st, int j, float tlf, float bsl, float rlo, float rhi) {
;     float sum = 0.f;
; #pragma unroll
;     for (int i = 0; i < 16; ++i) { const float tmp = (float)(32 * j - 64 + (i & 3) + 8 * (i >> 2)) + tlf;
;         float arg = __builtin_fmaf(-bsl, __builtin_fabsf(tmp), st[i]);
;         arg = (tmp >= rlo && tmp <= rhi) ? arg : -1.0e30f;
;         const float pe = __builtin_amdgcn_exp2f(arg); st[i] = pe; sum += pe; }
;     return sum;
; template <bool FUSED> __device__ __forceinline__ void attn_phase(const Args& a, LAS unsigned char* lds, int tid, int lane, int wave) {
;     ...
;         for (int j = 0; j < 5; ++j) {
;             f32x16 st;
; #pragma unroll
;             for (int i = 0; i < 16; ++i) st[i] = -mb;
;             LAS const unsigned char* kp = lds + (32 * wave + 32 * j + l31) * KP + 16 * h;
; #pragma unroll
;             for (int ks = 0; ks < 4; ++ks) { const bf16x8 kf = *(LAS const bf16x8*)(kp + 32 * ks); st = __builtin_amdgcn_mfma_f32_32x32x16_bf16(kf, qf[ks], st, 0, 0, 0); }
;             sum += attn_tile_exp(st, j, tlf, bsl, rlo, rhi);
; #pragma unroll
;             for (int s2 = 0; s2 < 2; ++s2) { u32x4 pw; pw.x = pk2(st[8 * s2 + 0], st[8 * s2 + 1]); pw.y = pk2(st[8 * s2 + 2], st[8 * s2 + 3]); pw.z = pk2(st[8 * s2 + 4], st[8 * s2 + 5]); pw.w = pk2(st[8 * s2 + 6], st[8 * s2 + 7]);
;                 const bf16x8 pf = __builtin_bit_cast(bf16x8, pw);
;                 LAS const unsigned char* vp = lds + LDS_VOFF + (32 * wave + 32 * j + 16 * s2 + 4 * h + q) * VP + 32 * blk + 8 * p;
; #pragma unroll
;                 for (int dt = 0; dt < 2; ++dt) { const s16x4 lo = trrd(vp + dt * 64), hi = trrd(vp + 8 * VP + dt * 64);
;                     const bf16x8 vf = __builtin_shufflevector(lo, hi, 0, 1, 2, 3, 4, 5, 6, 7);
;                     o[dt] = __builtin_amdgcn_mfma_f32_32x32x16_bf16(vf, pf, o[dt], 0, 0, 0); } }
;             __builtin_amdgcn_sched_barrier(0);
;         }
	ds_read_b128 v[226:229], v201
	ds_read_b128 v[230:233], v201 offset:32
	v_add_f32_e32 v239, 0xc2000000, v225
	v_add_f32_e32 v240, 0xc1f80000, v225
	s_waitcnt lgkmcnt(1)
	v_mfma_f32_32x32x16_bf16 v[48:63], v[226:229], v[136:139], v[0:15]
	ds_read_b128 v[226:229], v201 offset:64
	ds_read_b128 v[234:237], v201 offset:96
	v_add_f32_e32 v241, 0xc1f00000, v225
	v_add_f32_e32 v242, 0xc1e80000, v225
	s_waitcnt lgkmcnt(2)
	v_mfma_f32_32x32x16_bf16 v[48:63], v[230:233], v[132:135], v[48:63]
	v_add_f32_e32 v230, 0xc1c00000, v225
	v_add_f32_e32 v231, 0xc1b80000, v225
	s_waitcnt lgkmcnt(1)
	v_mfma_f32_32x32x16_bf16 v[48:63], v[226:229], v[128:131], v[48:63]
	s_waitcnt lgkmcnt(0)
	v_mfma_f32_32x32x16_bf16 v[48:63], v[234:237], v[140:143], v[48:63]
	s_nop 11
	v_fma_f32 v48, v224, |v239|, v48
	v_fma_f32 v49, v224, |v240|, v49
	v_fma_f32 v50, v224, |v241|, v50
	v_fma_f32 v51, v224, |v242|, v51
	v_fma_f32 v52, v224, |v230|, v52
	v_fma_f32 v53, v224, |v231|, v53
	v_exp_f32_e32 v227, v49
	v_mov_b32_e32 v49, v53
	v_exp_f32_e32 v231, v49
	v_add_f32_e32 v49, 0xc1b00000, v225
	v_exp_f32_e32 v228, v50
	v_fma_f32 v49, v224, |v49|, v54
	v_exp_f32_e32 v226, v48
	v_exp_f32_e32 v232, v49
	v_add_f32_e32 v49, 0xc1a80000, v225
	v_fma_f32 v49, v224, |v49|, v55
	v_exp_f32_e32 v229, v51
	v_exp_f32_e32 v230, v52
	v_add_f32_e32 v48, 0, v226
	v_exp_f32_e32 v55, v49
	v_add_f32_e32 v49, 0xc1800000, v225
	v_add_f32_e32 v48, v227, v48
	v_add_f32_e32 v48, v228, v48
	v_fma_f32 v49, v224, |v49|, v56
	v_add_f32_e32 v48, v229, v48
	v_add_f32_e32 v48, v230, v48
	v_exp_f32_e32 v233, v49
	v_add_f32_e32 v48, v231, v48
	v_add_f32_e32 v48, v232, v48
	v_add_f32_e32 v48, v55, v48
	v_add_f32_e32 v234, v233, v48
	v_add_f32_e32 v48, 0xc1700000, v225
	v_fma_f32 v48, v224, |v48|, v57
	v_exp_f32_e32 v235, v48
	v_add_f32_e32 v48, 0xc1600000, v225
	v_fma_f32 v48, v224, |v48|, v58
	v_exp_f32_e32 v236, v48
	v_add_f32_e32 v48, 0xc1500000, v225
	v_fma_f32 v48, v224, |v48|, v59
	v_exp_f32_e32 v237, v48
	v_add_f32_e32 v48, 0xc1000000, v225
	v_fma_f32 v48, v224, |v48|, v60
	v_exp_f32_e32 v60, v48
	v_add_f32_e32 v48, 0xc0e00000, v225
	v_fma_f32 v48, v224, |v48|, v61
	v_exp_f32_e32 v61, v48
	v_add_f32_e32 v48, 0xc0c00000, v225
	v_fma_f32 v52, v224, |v48|, v62
	ds_read_b64_tr_b16 v[48:49], v202 offset:55296
	ds_read_b64_tr_b16 v[50:51], v202 offset:56832
	ds_read_b64_tr_b16 v[58:59], v202 offset:56896
	ds_read_b64_tr_b16 v[56:57], v202 offset:55360
	v_exp_f32_e32 v62, v52
	v_add_f32_e32 v239, 0xc0a00000, v225
	v_cvt_pk_bf16_f32 v52, v226, v227
	v_cvt_pk_bf16_f32 v53, v228, v229
	v_cvt_pk_bf16_f32 v54, v230, v231
	v_cvt_pk_bf16_f32 v55, v232, v55
	s_waitcnt lgkmcnt(2)
	s_nop 0
	v_mfma_f32_32x32x16_bf16 v[32:47], v[48:51], v[52:55], v[32:47]
	v_fma_f32 v63, v224, |v239|, v63
	ds_read_b64_tr_b16 v[48:49], v202 offset:58368
	ds_read_b64_tr_b16 v[50:51], v202 offset:59904
	v_exp_f32_e32 v63, v63
	s_waitcnt lgkmcnt(2)
	v_mfma_f32_32x32x16_bf16 v[16:31], v[56:59], v[52:55], v[16:31]
	ds_read_b64_tr_b16 v[58:59], v202 offset:59968
	ds_read_b64_tr_b16 v[56:57], v202 offset:58432
	v_cvt_pk_bf16_f32 v52, v233, v235
	v_cvt_pk_bf16_f32 v53, v236, v237
	v_cvt_pk_bf16_f32 v54, v60, v61
	v_cvt_pk_bf16_f32 v55, v62, v63
	s_waitcnt lgkmcnt(2)
	s_nop 0
	v_mfma_f32_32x32x16_bf16 v[32:47], v[48:51], v[52:55], v[32:47]
	v_add_f32_e32 v48, v235, v234
	v_add_f32_e32 v48, v236, v48
	v_add_f32_e32 v48, v237, v48
	v_add_f32_e32 v48, v60, v48
	v_add_f32_e32 v48, v61, v48
	v_add_f32_e32 v48, v62, v48
	v_add_f32_e32 v48, v63, v48
	s_waitcnt lgkmcnt(0)
	v_mfma_f32_32x32x16_bf16 v[16:31], v[56:59], v[52:55], v[16:31]
	v_add_f32_e32 v238, v238, v48
	ds_read_b128 v[226:229], v203
	ds_read_b128 v[230:233], v203 offset:32
	v_add_f32_e32 v239, 1.0, v225
	s_waitcnt lgkmcnt(1)
	v_mfma_f32_32x32x16_bf16 v[48:63], v[226:229], v[136:139], v[0:15]
	ds_read_b128 v[226:229], v203 offset:64
	ds_read_b128 v[234:237], v203 offset:96
	s_waitcnt lgkmcnt(2)
	v_mfma_f32_32x32x16_bf16 v[48:63], v[230:233], v[132:135], v[48:63]
	v_add_f32_e32 v230, 2.0, v225
	v_add_f32_e32 v231, 0x40400000, v225
	v_add_f32_e32 v232, 0x41000000, v225
	s_waitcnt lgkmcnt(1)
	v_mfma_f32_32x32x16_bf16 v[48:63], v[226:229], v[128:131], v[48:63]
	v_add_f32_e32 v233, 0x41100000, v225
	s_waitcnt lgkmcnt(0)
	v_mfma_f32_32x32x16_bf16 v[48:63], v[234:237], v[140:143], v[48:63]
	s_nop 11
	v_fma_f32 v48, v224, |v225|, v48
	v_fma_f32 v49, v224, |v239|, v49
	v_fma_f32 v50, v224, |v230|, v50
	v_fma_f32 v51, v224, |v231|, v51
	v_fma_f32 v52, v224, |v232|, v52
	v_fma_f32 v53, v224, |v233|, v53
	v_exp_f32_e32 v227, v49
	v_mov_b32_e32 v49, v53
	v_exp_f32_e32 v231, v49
	v_add_f32_e32 v49, 0x41200000, v225
	v_exp_f32_e32 v228, v50
	v_fma_f32 v49, v224, |v49|, v54
	v_exp_f32_e32 v226, v48
	v_exp_f32_e32 v232, v49
	v_add_f32_e32 v49, 0x41300000, v225
	v_fma_f32 v49, v224, |v49|, v55
	v_exp_f32_e32 v229, v51
	v_exp_f32_e32 v230, v52
	v_add_f32_e32 v48, 0, v226
	v_exp_f32_e32 v55, v49
	v_add_f32_e32 v49, 0x41800000, v225
	v_add_f32_e32 v48, v227, v48
	v_add_f32_e32 v48, v228, v48
	v_fma_f32 v49, v224, |v49|, v56
	v_add_f32_e32 v48, v229, v48
	v_add_f32_e32 v48, v230, v48
	v_exp_f32_e32 v233, v49
	v_add_f32_e32 v48, v231, v48
	v_add_f32_e32 v48, v232, v48
	v_add_f32_e32 v48, v55, v48
	v_add_f32_e32 v234, v233, v48
	v_add_f32_e32 v48, 0x41880000, v225
	v_fma_f32 v48, v224, |v48|, v57
	v_exp_f32_e32 v235, v48
	v_add_f32_e32 v48, 0x41900000, v225
	v_fma_f32 v48, v224, |v48|, v58
	v_exp_f32_e32 v236, v48
	v_add_f32_e32 v48, 0x41980000, v225
	v_fma_f32 v48, v224, |v48|, v59
	v_exp_f32_e32 v237, v48
	v_add_f32_e32 v48, 0x41c00000, v225
	v_fma_f32 v48, v224, |v48|, v60
	v_exp_f32_e32 v60, v48
	v_add_f32_e32 v48, 0x41c80000, v225
	v_fma_f32 v48, v224, |v48|, v61
	v_exp_f32_e32 v61, v48
	v_add_f32_e32 v48, 0x41d00000, v225
	v_fma_f32 v52, v224, |v48|, v62
	ds_read_b64_tr_b16 v[48:49], v204 offset:55296
	ds_read_b64_tr_b16 v[50:51], v204 offset:56832
	ds_read_b64_tr_b16 v[58:59], v204 offset:56896
	ds_read_b64_tr_b16 v[56:57], v204 offset:55360
	v_exp_f32_e32 v62, v52
	v_add_f32_e32 v239, 0x41d80000, v225
	v_cvt_pk_bf16_f32 v52, v226, v227
	v_cvt_pk_bf16_f32 v53, v228, v229
	v_cvt_pk_bf16_f32 v54, v230, v231
	v_cvt_pk_bf16_f32 v55, v232, v55
	s_waitcnt lgkmcnt(2)
; #define LAS __attribute__((address_space(3)))
; __device__ __forceinline__ unsigned pk2(float lo, float hi) { f32x2_t v = {lo, hi}; bf16x2_t b = __builtin_convertvector(v, bf16x2_t); return __builtin_bit_cast(unsigned, b); }
; __device__ __forceinline__ s16x4 trrd(LAS const unsigned char* p) { return __builtin_bit_cast(s16x4, __builtin_amdgcn_ds_read_tr16_b64_v4i16((LAS v4i16_t*)p)); }
; __device__ __forceinline__ float attn_tile_exp(f32x16& st, int j, float tlf, float bsl, float rlo, float rhi) {
;     float sum = 0.f;
; #pragma unroll
;     for (int i = 0; i < 16; ++i) { const float tmp = (float)(32 * j - 64 + (i & 3) + 8 * (i >> 2)) + tlf;
;         float arg = __builtin_fmaf(-bsl, __builtin_fabsf(tmp), st[i]);
;         arg = (tmp >= rlo && tmp <= rhi) ? arg : -1.0e30f;
;         const float pe = __builtin_amdgcn_exp2f(arg); st[i] = pe; sum += pe; }
;     return sum;
; template <bool FUSED> __device__ __forceinline__ void attn_phase(const Args& a, LAS unsigned char* lds, int tid, int lane, int wave) {
;     ...
;         for (int j = 0; j < 5; ++j) {
;             f32x16 st;
; #pragma unroll
;             for (int i = 0; i < 16; ++i) st[i] = -mb;
;             LAS const unsigned char* kp = lds + (32 * wave + 32 * j + l31) * KP + 16 * h;
; #pragma unroll
;             for (int ks = 0; ks < 4; ++ks) { const bf16x8 kf = *(LAS const bf16x8*)(kp + 32 * ks); st = __builtin_amdgcn_mfma_f32_32x32x16_bf16(kf, qf[ks], st, 0, 0, 0); }
;             sum += attn_tile_exp(st, j, tlf, bsl, rlo, rhi);
; #pragma unroll
;             for (int s2 = 0; s2 < 2; ++s2) { u32x4 pw; pw.x = pk2(st[8 * s2 + 0], st[8 * s2 + 1]); pw.y = pk2(st[8 * s2 + 2], st[8 * s2 + 3]); pw.z = pk2(st[8 * s2 + 4], st[8 * s2 + 5]); pw.w = pk2(st[8 * s2 + 6], st[8 * s2 + 7]);
;                 const bf16x8 pf = __builtin_bit_cast(bf16x8, pw);
;                 LAS const unsigned char* vp = lds + LDS_VOFF + (32 * wave + 32 * j + 16 * s2 + 4 * h + q) * VP + 32 * blk + 8 * p;
; #pragma unroll
;                 for (int dt = 0; dt < 2; ++dt) { const s16x4 lo = trrd(vp + dt * 64), hi = trrd(vp + 8 * VP + dt * 64);
;                     const bf16x8 vf = __builtin_shufflevector(lo, hi, 0, 1, 2, 3, 4, 5, 6, 7);
;                     o[dt] = __builtin_amdgcn_mfma_f32_32x32x16_bf16(vf, pf, o[dt], 0, 0, 0); } }
;             __builtin_amdgcn_sched_barrier(0);
;         }
	s_nop 0
	v_mfma_f32_32x32x16_bf16 v[32:47], v[48:51], v[52:55], v[32:47]
	v_fma_f32 v63, v224, |v239|, v63
	ds_read_b64_tr_b16 v[48:49], v204 offset:58368
	ds_read_b64_tr_b16 v[50:51], v204 offset:59904
	v_exp_f32_e32 v63, v63
	s_waitcnt lgkmcnt(2)
	v_mfma_f32_32x32x16_bf16 v[16:31], v[56:59], v[52:55], v[16:31]
	ds_read_b64_tr_b16 v[58:59], v204 offset:59968
	ds_read_b64_tr_b16 v[56:57], v204 offset:58432
	v_cvt_pk_bf16_f32 v52, v233, v235
	v_cvt_pk_bf16_f32 v53, v236, v237
	v_cvt_pk_bf16_f32 v54, v60, v61
	v_cvt_pk_bf16_f32 v55, v62, v63
	s_waitcnt lgkmcnt(2)
	s_nop 0
	v_mfma_f32_32x32x16_bf16 v[32:47], v[48:51], v[52:55], v[32:47]
	v_add_f32_e32 v48, v235, v234
	v_add_f32_e32 v48, v236, v48
	v_add_f32_e32 v48, v237, v48
	v_add_f32_e32 v48, v60, v48
	v_add_f32_e32 v48, v61, v48
	v_add_f32_e32 v48, v62, v48
	v_add_f32_e32 v48, v63, v48
	s_waitcnt lgkmcnt(0)
	v_mfma_f32_32x32x16_bf16 v[16:31], v[56:59], v[52:55], v[16:31]
	v_add_f32_e32 v238, v238, v48
	ds_read_b128 v[226:229], v205
	ds_read_b128 v[230:233], v205 offset:32
	v_add_f32_e32 v239, 0x42000000, v225
	v_add_f32_e32 v240, 0x42040000, v225
	s_waitcnt lgkmcnt(1)
	v_mfma_f32_32x32x16_bf16 v[48:63], v[226:229], v[136:139], v[0:15]
	ds_read_b128 v[226:229], v205 offset:64
	ds_read_b128 v[234:237], v205 offset:96
	v_add_f32_e32 v241, 0x42080000, v225
	v_add_f32_e32 v242, 0x420c0000, v225
	s_waitcnt lgkmcnt(2)
	v_mfma_f32_32x32x16_bf16 v[48:63], v[230:233], v[132:135], v[48:63]
	v_add_f32_e32 v230, 0x42200000, v225
	v_add_f32_e32 v231, 0x42240000, v225
	s_waitcnt lgkmcnt(1)
	v_mfma_f32_32x32x16_bf16 v[48:63], v[226:229], v[128:131], v[48:63]
	s_waitcnt lgkmcnt(0)
	v_mfma_f32_32x32x16_bf16 v[48:63], v[234:237], v[140:143], v[48:63]
	s_nop 11
	v_fma_f32 v48, v224, |v239|, v48
	v_fma_f32 v49, v224, |v240|, v49
	v_fma_f32 v50, v224, |v241|, v50
	v_fma_f32 v51, v224, |v242|, v51
	v_fma_f32 v52, v224, |v230|, v52
	v_fma_f32 v53, v224, |v231|, v53
	v_exp_f32_e32 v227, v49
	v_mov_b32_e32 v49, v53
	v_exp_f32_e32 v231, v49
	v_add_f32_e32 v49, 0x42280000, v225
	v_exp_f32_e32 v228, v50
	v_fma_f32 v49, v224, |v49|, v54
	v_exp_f32_e32 v226, v48
	v_exp_f32_e32 v232, v49
	v_add_f32_e32 v49, 0x422c0000, v225
	v_fma_f32 v49, v224, |v49|, v55
	v_exp_f32_e32 v229, v51
	v_exp_f32_e32 v230, v52
	v_add_f32_e32 v48, 0, v226
	v_exp_f32_e32 v55, v49
	v_add_f32_e32 v49, 0x42400000, v225
	v_add_f32_e32 v48, v227, v48
	v_add_f32_e32 v48, v228, v48
	v_fma_f32 v49, v224, |v49|, v56
	v_add_f32_e32 v48, v229, v48
	v_add_f32_e32 v48, v230, v48
	v_exp_f32_e32 v233, v49
	v_add_f32_e32 v48, v231, v48
	v_add_f32_e32 v48, v232, v48
	v_add_f32_e32 v48, v55, v48
	v_add_f32_e32 v234, v233, v48
	v_add_f32_e32 v48, 0x42440000, v225
	v_fma_f32 v48, v224, |v48|, v57
	v_exp_f32_e32 v235, v48
	v_add_f32_e32 v48, 0x42480000, v225
	v_fma_f32 v48, v224, |v48|, v58
	v_exp_f32_e32 v236, v48
	v_add_f32_e32 v48, 0x424c0000, v225
	v_fma_f32 v48, v224, |v48|, v59
	v_exp_f32_e32 v237, v48
	v_add_f32_e32 v48, 0x42600000, v225
	v_fma_f32 v48, v224, |v48|, v60
	v_exp_f32_e32 v60, v48
	v_add_f32_e32 v48, 0x42640000, v225
	v_fma_f32 v48, v224, |v48|, v61
	v_exp_f32_e32 v61, v48
	v_add_f32_e32 v48, 0x42680000, v225
	v_fma_f32 v52, v224, |v48|, v62
	ds_read_b64_tr_b16 v[48:49], v206 offset:55296
	ds_read_b64_tr_b16 v[50:51], v206 offset:56832
	ds_read_b64_tr_b16 v[58:59], v206 offset:56896
	ds_read_b64_tr_b16 v[56:57], v206 offset:55360
	v_exp_f32_e32 v62, v52
	v_add_f32_e32 v239, 0x426c0000, v225
	v_cvt_pk_bf16_f32 v52, v226, v227
	v_cvt_pk_bf16_f32 v53, v228, v229
	v_cvt_pk_bf16_f32 v54, v230, v231
	v_cvt_pk_bf16_f32 v55, v232, v55
	s_waitcnt lgkmcnt(2)
	s_nop 0
	v_mfma_f32_32x32x16_bf16 v[32:47], v[48:51], v[52:55], v[32:47]
	v_fma_f32 v63, v224, |v239|, v63
	ds_read_b64_tr_b16 v[48:49], v206 offset:58368
	ds_read_b64_tr_b16 v[50:51], v206 offset:59904
	v_exp_f32_e32 v63, v63
	s_waitcnt lgkmcnt(2)
	v_mfma_f32_32x32x16_bf16 v[16:31], v[56:59], v[52:55], v[16:31]
	ds_read_b64_tr_b16 v[58:59], v206 offset:59968
	ds_read_b64_tr_b16 v[56:57], v206 offset:58432
	v_cvt_pk_bf16_f32 v52, v233, v235
	v_cvt_pk_bf16_f32 v53, v236, v237
	v_cvt_pk_bf16_f32 v54, v60, v61
	v_cvt_pk_bf16_f32 v55, v62, v63
	s_waitcnt lgkmcnt(2)
	s_nop 0
	v_mfma_f32_32x32x16_bf16 v[32:47], v[48:51], v[52:55], v[32:47]
	v_add_f32_e32 v48, v235, v234
	v_add_f32_e32 v48, v236, v48
	v_add_f32_e32 v48, v237, v48
	v_add_f32_e32 v48, v60, v48
	v_add_f32_e32 v48, v61, v48
	v_add_f32_e32 v48, v62, v48
	v_add_f32_e32 v48, v63, v48
	s_waitcnt lgkmcnt(0)
	v_mfma_f32_32x32x16_bf16 v[16:31], v[56:59], v[52:55], v[16:31]
	v_add_f32_e32 v60, v238, v48
	s_branch .Lattn1_t4
; #define LAS __attribute__((address_space(3)))
; __device__ __forceinline__ unsigned pk2(float lo, float hi) { f32x2_t v = {lo, hi}; bf16x2_t b = __builtin_convertvector(v, bf16x2_t); return __builtin_bit_cast(unsigned, b); }
; __device__ __forceinline__ s16x4 trrd(LAS const unsigned char* p) { return __builtin_bit_cast(s16x4, __builtin_amdgcn_ds_read_tr16_b64_v4i16((LAS v4i16_t*)p)); }
; __device__ __forceinline__ float attn_tile_exp(f32x16& st, int j, float tlf, float bsl, float rlo, float rhi) {
;     float sum = 0.f;
; #pragma unroll
;     for (int i = 0; i < 16; ++i) { const float tmp = (float)(32 * j - 64 + (i & 3) + 8 * (i >> 2)) + tlf;
;         float arg = __builtin_fmaf(-bsl, __builtin_fabsf(tmp), st[i]);
;         arg = (tmp >= rlo && tmp <= rhi) ? arg : -1.0e30f;
;         const float pe = __builtin_amdgcn_exp2f(arg); st[i] = pe; sum += pe; }
;     return sum;
; template <bool FUSED> __device__ __forceinline__ void attn_phase(const Args& a, LAS unsigned char* lds, int tid, int lane, int wave) {
;     ...
;         for (int j = 0; j < 5; ++j) {
;             f32x16 st;
; #pragma unroll
;             for (int i = 0; i < 16; ++i) st[i] = -mb;
;             LAS const unsigned char* kp = lds + (32 * wave + 32 * j + l31) * KP + 16 * h;
; #pragma unroll
;             for (int ks = 0; ks < 4; ++ks) { const bf16x8 kf = *(LAS const bf16x8*)(kp + 32 * ks); st = __builtin_amdgcn_mfma_f32_32x32x16_bf16(kf, qf[ks], st, 0, 0, 0); }
;             sum += attn_tile_exp(st, j, tlf, bsl, rlo, rhi);
; #pragma unroll
;             for (int s2 = 0; s2 < 2; ++s2) { u32x4 pw; pw.x = pk2(st[8 * s2 + 0], st[8 * s2 + 1]); pw.y = pk2(st[8 * s2 + 2], st[8 * s2 + 3]); pw.z = pk2(st[8 * s2 + 4], st[8 * s2 + 5]); pw.w = pk2(st[8 * s2 + 6], st[8 * s2 + 7]);
;                 const bf16x8 pf = __builtin_bit_cast(bf16x8, pw);
;                 LAS const unsigned char* vp = lds + LDS_VOFF + (32 * wave + 32 * j + 16 * s2 + 4 * h + q) * VP + 32 * blk + 8 * p;
; #pragma unroll
;                 for (int dt = 0; dt < 2; ++dt) { const s16x4 lo = trrd(vp + dt * 64), hi = trrd(vp + 8 * VP + dt * 64);
;                     const bf16x8 vf = __builtin_shufflevector(lo, hi, 0, 1, 2, 3, 4, 5, 6, 7);
;                     o[dt] = __builtin_amdgcn_mfma_f32_32x32x16_bf16(vf, pf, o[dt], 0, 0, 0); } }
;             __builtin_amdgcn_sched_barrier(0);
;         }
.Lattn1_slow:
	ds_read_b128 v[226:229], v201
	ds_read_b128 v[230:233], v201 offset:32
	v_add_f32_e32 v239, 0xc2000000, v225
	v_add_f32_e32 v240, 0xc1f80000, v225
	v_cmp_nge_f32_e32 vcc, v239, v169
	s_waitcnt lgkmcnt(1)
	v_mfma_f32_32x32x16_bf16 v[48:63], v[226:229], v[136:139], v[0:15]
	ds_read_b128 v[226:229], v201 offset:64
	ds_read_b128 v[234:237], v201 offset:96
	v_cmp_nle_f32_e64 s[6:7], v239, v223
	v_add_f32_e32 v241, 0xc1f00000, v225
	v_cmp_nge_f32_e64 s[8:9], v240, v169
	v_cmp_nle_f32_e64 s[10:11], v240, v223
	s_or_b64 vcc, vcc, s[6:7]
	v_add_f32_e32 v242, 0xc1e80000, v225
	s_waitcnt lgkmcnt(2)
	v_mfma_f32_32x32x16_bf16 v[48:63], v[230:233], v[132:135], v[48:63]
	v_cmp_nge_f32_e64 s[12:13], v241, v169
	v_cmp_nle_f32_e64 s[14:15], v241, v223
	v_add_f32_e32 v230, 0xc1c00000, v225
	v_cmp_nge_f32_e64 s[16:17], v242, v169
	v_cmp_nle_f32_e64 s[20:21], v242, v223
	v_add_f32_e32 v231, 0xc1b80000, v225
	v_cmp_nge_f32_e64 s[22:23], v230, v169
	s_waitcnt lgkmcnt(1)
	v_mfma_f32_32x32x16_bf16 v[48:63], v[226:229], v[128:131], v[48:63]
	v_cmp_nle_f32_e64 s[24:25], v230, v223
	v_cmp_nge_f32_e64 s[26:27], v231, v169
	v_cmp_nle_f32_e64 s[28:29], v231, v223
	s_waitcnt lgkmcnt(0)
	v_mfma_f32_32x32x16_bf16 v[48:63], v[234:237], v[140:143], v[48:63]
	s_nop 11
	v_fma_f32 v48, v224, |v239|, v48
	v_fma_f32 v49, v224, |v240|, v49
	v_cndmask_b32_e32 v48, v48, v221, vcc
	s_or_b64 vcc, s[8:9], s[10:11]
	v_fma_f32 v50, v224, |v241|, v50
	v_cndmask_b32_e32 v49, v49, v221, vcc
	s_or_b64 vcc, s[12:13], s[14:15]
	v_fma_f32 v51, v224, |v242|, v51
	v_cndmask_b32_e32 v50, v50, v221, vcc
	s_or_b64 vcc, s[16:17], s[20:21]
	v_fma_f32 v52, v224, |v230|, v52
	v_cndmask_b32_e32 v51, v51, v221, vcc
	s_or_b64 vcc, s[22:23], s[24:25]
	v_fma_f32 v53, v224, |v231|, v53
	v_cndmask_b32_e32 v52, v52, v221, vcc
	s_or_b64 vcc, s[26:27], s[28:29]
	v_exp_f32_e32 v227, v49
	v_cndmask_b32_e32 v49, v53, v221, vcc
	v_exp_f32_e32 v231, v49
	v_add_f32_e32 v49, 0xc1b00000, v225
	v_cmp_nge_f32_e32 vcc, v49, v169
	v_cmp_nle_f32_e64 s[6:7], v49, v223
	v_exp_f32_e32 v228, v50
	v_fma_f32 v50, v224, |v49|, v54
	s_or_b64 vcc, vcc, s[6:7]
	v_cndmask_b32_e32 v49, v50, v221, vcc
	v_exp_f32_e32 v226, v48
	v_exp_f32_e32 v232, v49
	v_add_f32_e32 v49, 0xc1a80000, v225
	v_cmp_nge_f32_e32 vcc, v49, v169
	v_cmp_nle_f32_e64 s[6:7], v49, v223
	v_fma_f32 v50, v224, |v49|, v55
	s_or_b64 vcc, vcc, s[6:7]
	v_exp_f32_e32 v229, v51
	v_cndmask_b32_e32 v49, v50, v221, vcc
	v_exp_f32_e32 v230, v52
	v_add_f32_e32 v48, 0, v226
	v_exp_f32_e32 v55, v49
	v_add_f32_e32 v49, 0xc1800000, v225
	v_add_f32_e32 v48, v227, v48
	v_cmp_nge_f32_e32 vcc, v49, v169
	v_cmp_nle_f32_e64 s[6:7], v49, v223
	v_add_f32_e32 v48, v228, v48
	v_fma_f32 v50, v224, |v49|, v56
	s_or_b64 vcc, vcc, s[6:7]
	v_add_f32_e32 v48, v229, v48
	v_cndmask_b32_e32 v49, v50, v221, vcc
	v_add_f32_e32 v48, v230, v48
	v_exp_f32_e32 v233, v49
	v_add_f32_e32 v48, v231, v48
	v_add_f32_e32 v48, v232, v48
	v_add_f32_e32 v48, v55, v48
	v_add_f32_e32 v234, v233, v48
	v_add_f32_e32 v48, 0xc1700000, v225
	v_cmp_nge_f32_e32 vcc, v48, v169
	v_cmp_nle_f32_e64 s[6:7], v48, v223
	v_fma_f32 v49, v224, |v48|, v57
	s_or_b64 vcc, vcc, s[6:7]
	v_cndmask_b32_e32 v48, v49, v221, vcc
	v_exp_f32_e32 v235, v48
	v_add_f32_e32 v48, 0xc1600000, v225
	v_cmp_nge_f32_e32 vcc, v48, v169
	v_cmp_nle_f32_e64 s[6:7], v48, v223
	v_fma_f32 v49, v224, |v48|, v58
	s_or_b64 vcc, vcc, s[6:7]
	v_cndmask_b32_e32 v48, v49, v221, vcc
	v_exp_f32_e32 v236, v48
	v_add_f32_e32 v48, 0xc1500000, v225
	v_cmp_nge_f32_e32 vcc, v48, v169
	v_cmp_nle_f32_e64 s[6:7], v48, v223
	v_fma_f32 v49, v224, |v48|, v59
	s_or_b64 vcc, vcc, s[6:7]
	v_cndmask_b32_e32 v48, v49, v221, vcc
	v_exp_f32_e32 v237, v48
	v_add_f32_e32 v48, 0xc1000000, v225
	v_cmp_nge_f32_e32 vcc, v48, v169
	v_cmp_nle_f32_e64 s[6:7], v48, v223
	v_fma_f32 v49, v224, |v48|, v60
	s_or_b64 vcc, vcc, s[6:7]
	v_cndmask_b32_e32 v48, v49, v221, vcc
	v_exp_f32_e32 v60, v48
	v_add_f32_e32 v48, 0xc0e00000, v225
	v_cmp_nge_f32_e32 vcc, v48, v169
	v_cmp_nle_f32_e64 s[6:7], v48, v223
	v_fma_f32 v49, v224, |v48|, v61
	s_or_b64 vcc, vcc, s[6:7]
	v_cndmask_b32_e32 v48, v49, v221, vcc
	v_exp_f32_e32 v61, v48
	v_add_f32_e32 v48, 0xc0c00000, v225
	v_cmp_nge_f32_e32 vcc, v48, v169
	v_cmp_nle_f32_e64 s[6:7], v48, v223
	v_fma_f32 v49, v224, |v48|, v62
	s_or_b64 vcc, vcc, s[6:7]
	v_cndmask_b32_e32 v52, v49, v221, vcc
	ds_read_b64_tr_b16 v[48:49], v202 offset:55296
	ds_read_b64_tr_b16 v[50:51], v202 offset:56832
	ds_read_b64_tr_b16 v[58:59], v202 offset:56896
	ds_read_b64_tr_b16 v[56:57], v202 offset:55360
	v_exp_f32_e32 v62, v52
	v_add_f32_e32 v239, 0xc0a00000, v225
	v_cvt_pk_bf16_f32 v52, v226, v227
	v_cvt_pk_bf16_f32 v53, v228, v229
	v_cvt_pk_bf16_f32 v54, v230, v231
	v_cvt_pk_bf16_f32 v55, v232, v55
	v_cmp_nge_f32_e32 vcc, v239, v169
	v_cmp_nle_f32_e64 s[6:7], v239, v223
	s_waitcnt lgkmcnt(2)
	v_mfma_f32_32x32x16_bf16 v[32:47], v[48:51], v[52:55], v[32:47]
	v_fma_f32 v48, v224, |v239|, v63
	s_or_b64 vcc, vcc, s[6:7]
	v_cndmask_b32_e32 v63, v48, v221, vcc
	ds_read_b64_tr_b16 v[48:49], v202 offset:58368
	ds_read_b64_tr_b16 v[50:51], v202 offset:59904
	v_exp_f32_e32 v63, v63
	s_waitcnt lgkmcnt(2)
	v_mfma_f32_32x32x16_bf16 v[16:31], v[56:59], v[52:55], v[16:31]
	ds_read_b64_tr_b16 v[58:59], v202 offset:59968
	ds_read_b64_tr_b16 v[56:57], v202 offset:58432
	v_cvt_pk_bf16_f32 v52, v233, v235
	v_cvt_pk_bf16_f32 v53, v236, v237
	v_cvt_pk_bf16_f32 v54, v60, v61
	v_cvt_pk_bf16_f32 v55, v62, v63
	s_waitcnt lgkmcnt(2)
	s_nop 0
	v_mfma_f32_32x32x16_bf16 v[32:47], v[48:51], v[52:55], v[32:47]
	v_add_f32_e32 v48, v235, v234
	v_add_f32_e32 v48, v236, v48
	v_add_f32_e32 v48, v237, v48
	v_add_f32_e32 v48, v60, v48
	v_add_f32_e32 v48, v61, v48
	v_add_f32_e32 v48, v62, v48
	v_add_f32_e32 v48, v63, v48
	s_waitcnt lgkmcnt(0)
; #define LAS __attribute__((address_space(3)))
; __device__ __forceinline__ unsigned pk2(float lo, float hi) { f32x2_t v = {lo, hi}; bf16x2_t b = __builtin_convertvector(v, bf16x2_t); return __builtin_bit_cast(unsigned, b); }
; __device__ __forceinline__ s16x4 trrd(LAS const unsigned char* p) { return __builtin_bit_cast(s16x4, __builtin_amdgcn_ds_read_tr16_b64_v4i16((LAS v4i16_t*)p)); }
; __device__ __forceinline__ float attn_tile_exp(f32x16& st, int j, float tlf, float bsl, float rlo, float rhi) {
;     float sum = 0.f;
; #pragma unroll
;     for (int i = 0; i < 16; ++i) { const float tmp = (float)(32 * j - 64 + (i & 3) + 8 * (i >> 2)) + tlf;
;         float arg = __builtin_fmaf(-bsl, __builtin_fabsf(tmp), st[i]);
;         arg = (tmp >= rlo && tmp <= rhi) ? arg : -1.0e30f;
;         const float pe = __builtin_amdgcn_exp2f(arg); st[i] = pe; sum += pe; }
;     return sum;
; template <bool FUSED> __device__ __forceinline__ void attn_phase(const Args& a, LAS unsigned char* lds, int tid, int lane, int wave) {
;     ...
;         for (int j = 0; j < 5; ++j) {
;             f32x16 st;
; #pragma unroll
;             for (int i = 0; i < 16; ++i) st[i] = -mb;
;             LAS const unsigned char* kp = lds + (32 * wave + 32 * j + l31) * KP + 16 * h;
; #pragma unroll
;             for (int ks = 0; ks < 4; ++ks) { const bf16x8 kf = *(LAS const bf16x8*)(kp + 32 * ks); st = __builtin_amdgcn_mfma_f32_32x32x16_bf16(kf, qf[ks], st, 0, 0, 0); }
;             sum += attn_tile_exp(st, j, tlf, bsl, rlo, rhi);
; #pragma unroll
;             for (int s2 = 0; s2 < 2; ++s2) { u32x4 pw; pw.x = pk2(st[8 * s2 + 0], st[8 * s2 + 1]); pw.y = pk2(st[8 * s2 + 2], st[8 * s2 + 3]); pw.z = pk2(st[8 * s2 + 4], st[8 * s2 + 5]); pw.w = pk2(st[8 * s2 + 6], st[8 * s2 + 7]);
;                 const bf16x8 pf = __builtin_bit_cast(bf16x8, pw);
;                 LAS const unsigned char* vp = lds + LDS_VOFF + (32 * wave + 32 * j + 16 * s2 + 4 * h + q) * VP + 32 * blk + 8 * p;
; #pragma unroll
;                 for (int dt = 0; dt < 2; ++dt) { const s16x4 lo = trrd(vp + dt * 64), hi = trrd(vp + 8 * VP + dt * 64);
;                     const bf16x8 vf = __builtin_shufflevector(lo, hi, 0, 1, 2, 3, 4, 5, 6, 7);
;                     o[dt] = __builtin_amdgcn_mfma_f32_32x32x16_bf16(vf, pf, o[dt], 0, 0, 0); } }
;             __builtin_amdgcn_sched_barrier(0);
;         }
	v_mfma_f32_32x32x16_bf16 v[16:31], v[56:59], v[52:55], v[16:31]
	v_add_f32_e32 v238, v238, v48
	ds_read_b128 v[226:229], v203
	ds_read_b128 v[230:233], v203 offset:32
	v_cmp_nge_f32_e32 vcc, v225, v169
	v_cmp_nle_f32_e64 s[6:7], v225, v223
	v_add_f32_e32 v239, 1.0, v225
	s_waitcnt lgkmcnt(1)
	v_mfma_f32_32x32x16_bf16 v[48:63], v[226:229], v[136:139], v[0:15]
	ds_read_b128 v[226:229], v203 offset:64
	ds_read_b128 v[234:237], v203 offset:96
	v_cmp_nge_f32_e64 s[8:9], v239, v169
	v_cmp_nle_f32_e64 s[10:11], v239, v223
	s_or_b64 vcc, vcc, s[6:7]
	s_waitcnt lgkmcnt(2)
	v_mfma_f32_32x32x16_bf16 v[48:63], v[230:233], v[132:135], v[48:63]
	v_add_f32_e32 v230, 2.0, v225
	v_add_f32_e32 v231, 0x40400000, v225
	v_cmp_nge_f32_e64 s[12:13], v230, v169
	v_cmp_nle_f32_e64 s[14:15], v230, v223
	v_add_f32_e32 v232, 0x41000000, v225
	v_cmp_nge_f32_e64 s[16:17], v231, v169
	v_cmp_nle_f32_e64 s[20:21], v231, v223
	s_waitcnt lgkmcnt(1)
	v_mfma_f32_32x32x16_bf16 v[48:63], v[226:229], v[128:131], v[48:63]
	v_add_f32_e32 v233, 0x41100000, v225
	v_cmp_nge_f32_e64 s[22:23], v232, v169
	v_cmp_nle_f32_e64 s[24:25], v232, v223
	v_cmp_nge_f32_e64 s[26:27], v233, v169
	v_cmp_nle_f32_e64 s[28:29], v233, v223
	s_waitcnt lgkmcnt(0)
	v_mfma_f32_32x32x16_bf16 v[48:63], v[234:237], v[140:143], v[48:63]
	s_nop 11
	v_fma_f32 v48, v224, |v225|, v48
	v_fma_f32 v49, v224, |v239|, v49
	v_cndmask_b32_e32 v48, v48, v221, vcc
	s_or_b64 vcc, s[8:9], s[10:11]
	v_fma_f32 v50, v224, |v230|, v50
	v_cndmask_b32_e32 v49, v49, v221, vcc
	s_or_b64 vcc, s[12:13], s[14:15]
	v_fma_f32 v51, v224, |v231|, v51
	v_cndmask_b32_e32 v50, v50, v221, vcc
	s_or_b64 vcc, s[16:17], s[20:21]
	v_fma_f32 v52, v224, |v232|, v52
	v_cndmask_b32_e32 v51, v51, v221, vcc
	s_or_b64 vcc, s[22:23], s[24:25]
	v_fma_f32 v53, v224, |v233|, v53
	v_cndmask_b32_e32 v52, v52, v221, vcc
	s_or_b64 vcc, s[26:27], s[28:29]
	v_exp_f32_e32 v227, v49
	v_cndmask_b32_e32 v49, v53, v221, vcc
	v_exp_f32_e32 v231, v49
	v_add_f32_e32 v49, 0x41200000, v225
	v_cmp_nge_f32_e32 vcc, v49, v169
	v_cmp_nle_f32_e64 s[6:7], v49, v223
	v_exp_f32_e32 v228, v50
	v_fma_f32 v50, v224, |v49|, v54
	s_or_b64 vcc, vcc, s[6:7]
	v_cndmask_b32_e32 v49, v50, v221, vcc
	v_exp_f32_e32 v226, v48
	v_exp_f32_e32 v232, v49
	v_add_f32_e32 v49, 0x41300000, v225
	v_cmp_nge_f32_e32 vcc, v49, v169
	v_cmp_nle_f32_e64 s[6:7], v49, v223
	v_fma_f32 v50, v224, |v49|, v55
	s_or_b64 vcc, vcc, s[6:7]
	v_exp_f32_e32 v229, v51
	v_cndmask_b32_e32 v49, v50, v221, vcc
	v_exp_f32_e32 v230, v52
	v_add_f32_e32 v48, 0, v226
	v_exp_f32_e32 v55, v49
	v_add_f32_e32 v49, 0x41800000, v225
	v_add_f32_e32 v48, v227, v48
	v_cmp_nge_f32_e32 vcc, v49, v169
	v_cmp_nle_f32_e64 s[6:7], v49, v223
	v_add_f32_e32 v48, v228, v48
	v_fma_f32 v50, v224, |v49|, v56
	s_or_b64 vcc, vcc, s[6:7]
	v_add_f32_e32 v48, v229, v48
	v_cndmask_b32_e32 v49, v50, v221, vcc
	v_add_f32_e32 v48, v230, v48
	v_exp_f32_e32 v233, v49
	v_add_f32_e32 v48, v231, v48
	v_add_f32_e32 v48, v232, v48
	v_add_f32_e32 v48, v55, v48
	v_add_f32_e32 v234, v233, v48
	v_add_f32_e32 v48, 0x41880000, v225
	v_cmp_nge_f32_e32 vcc, v48, v169
	v_cmp_nle_f32_e64 s[6:7], v48, v223
	v_fma_f32 v49, v224, |v48|, v57
	s_or_b64 vcc, vcc, s[6:7]
	v_cndmask_b32_e32 v48, v49, v221, vcc
	v_exp_f32_e32 v235, v48
	v_add_f32_e32 v48, 0x41900000, v225
	v_cmp_nge_f32_e32 vcc, v48, v169
	v_cmp_nle_f32_e64 s[6:7], v48, v223
	v_fma_f32 v49, v224, |v48|, v58
	s_or_b64 vcc, vcc, s[6:7]
	v_cndmask_b32_e32 v48, v49, v221, vcc
	v_exp_f32_e32 v236, v48
	v_add_f32_e32 v48, 0x41980000, v225
	v_cmp_nge_f32_e32 vcc, v48, v169
	v_cmp_nle_f32_e64 s[6:7], v48, v223
	v_fma_f32 v49, v224, |v48|, v59
	s_or_b64 vcc, vcc, s[6:7]
	v_cndmask_b32_e32 v48, v49, v221, vcc
	v_exp_f32_e32 v237, v48
	v_add_f32_e32 v48, 0x41c00000, v225
	v_cmp_nge_f32_e32 vcc, v48, v169
	v_cmp_nle_f32_e64 s[6:7], v48, v223
	v_fma_f32 v49, v224, |v48|, v60
	s_or_b64 vcc, vcc, s[6:7]
	v_cndmask_b32_e32 v48, v49, v221, vcc
	v_exp_f32_e32 v60, v48
	v_add_f32_e32 v48, 0x41c80000, v225
	v_cmp_nge_f32_e32 vcc, v48, v169
	v_cmp_nle_f32_e64 s[6:7], v48, v223
	v_fma_f32 v49, v224, |v48|, v61
	s_or_b64 vcc, vcc, s[6:7]
	v_cndmask_b32_e32 v48, v49, v221, vcc
	v_exp_f32_e32 v61, v48
	v_add_f32_e32 v48, 0x41d00000, v225
	v_cmp_nge_f32_e32 vcc, v48, v169
	v_cmp_nle_f32_e64 s[6:7], v48, v223
	v_fma_f32 v49, v224, |v48|, v62
	s_or_b64 vcc, vcc, s[6:7]
	v_cndmask_b32_e32 v52, v49, v221, vcc
	ds_read_b64_tr_b16 v[48:49], v204 offset:55296
	ds_read_b64_tr_b16 v[50:51], v204 offset:56832
	ds_read_b64_tr_b16 v[58:59], v204 offset:56896
	ds_read_b64_tr_b16 v[56:57], v204 offset:55360
	v_exp_f32_e32 v62, v52
	v_add_f32_e32 v239, 0x41d80000, v225
	v_cvt_pk_bf16_f32 v52, v226, v227
	v_cvt_pk_bf16_f32 v53, v228, v229
	v_cvt_pk_bf16_f32 v54, v230, v231
	v_cvt_pk_bf16_f32 v55, v232, v55
	v_cmp_nge_f32_e32 vcc, v239, v169
	v_cmp_nle_f32_e64 s[6:7], v239, v223
	s_waitcnt lgkmcnt(2)
	v_mfma_f32_32x32x16_bf16 v[32:47], v[48:51], v[52:55], v[32:47]
	v_fma_f32 v48, v224, |v239|, v63
	s_or_b64 vcc, vcc, s[6:7]
	v_cndmask_b32_e32 v63, v48, v221, vcc
	ds_read_b64_tr_b16 v[48:49], v204 offset:58368
	ds_read_b64_tr_b16 v[50:51], v204 offset:59904
	v_exp_f32_e32 v63, v63
	s_waitcnt lgkmcnt(2)
	v_mfma_f32_32x32x16_bf16 v[16:31], v[56:59], v[52:55], v[16:31]
	ds_read_b64_tr_b16 v[58:59], v204 offset:59968
	ds_read_b64_tr_b16 v[56:57], v204 offset:58432
	v_cvt_pk_bf16_f32 v52, v233, v235
	v_cvt_pk_bf16_f32 v53, v236, v237
	v_cvt_pk_bf16_f32 v54, v60, v61
	v_cvt_pk_bf16_f32 v55, v62, v63
	s_waitcnt lgkmcnt(2)
; #define LAS __attribute__((address_space(3)))
; __device__ __forceinline__ unsigned pk2(float lo, float hi) { f32x2_t v = {lo, hi}; bf16x2_t b = __builtin_convertvector(v, bf16x2_t); return __builtin_bit_cast(unsigned, b); }
; __device__ __forceinline__ s16x4 trrd(LAS const unsigned char* p) { return __builtin_bit_cast(s16x4, __builtin_amdgcn_ds_read_tr16_b64_v4i16((LAS v4i16_t*)p)); }
; __device__ __forceinline__ float attn_tile_exp(f32x16& st, int j, float tlf, float bsl, float rlo, float rhi) {
;     float sum = 0.f;
; #pragma unroll
;     for (int i = 0; i < 16; ++i) { const float tmp = (float)(32 * j - 64 + (i & 3) + 8 * (i >> 2)) + tlf;
;         float arg = __builtin_fmaf(-bsl, __builtin_fabsf(tmp), st[i]);
;         arg = (tmp >= rlo && tmp <= rhi) ? arg : -1.0e30f;
;         const float pe = __builtin_amdgcn_exp2f(arg); st[i] = pe; sum += pe; }
;     return sum;
; template <bool FUSED> __device__ __forceinline__ void attn_phase(const Args& a, LAS unsigned char* lds, int tid, int lane, int wave) {
;     ...
;         for (int j = 0; j < 5; ++j) {
;             f32x16 st;
; #pragma unroll
;             for (int i = 0; i < 16; ++i) st[i] = -mb;
;             LAS const unsigned char* kp = lds + (32 * wave + 32 * j + l31) * KP + 16 * h;
; #pragma unroll
;             for (int ks = 0; ks < 4; ++ks) { const bf16x8 kf = *(LAS const bf16x8*)(kp + 32 * ks); st = __builtin_amdgcn_mfma_f32_32x32x16_bf16(kf, qf[ks], st, 0, 0, 0); }
;             sum += attn_tile_exp(st, j, tlf, bsl, rlo, rhi);
; #pragma unroll
;             for (int s2 = 0; s2 < 2; ++s2) { u32x4 pw; pw.x = pk2(st[8 * s2 + 0], st[8 * s2 + 1]); pw.y = pk2(st[8 * s2 + 2], st[8 * s2 + 3]); pw.z = pk2(st[8 * s2 + 4], st[8 * s2 + 5]); pw.w = pk2(st[8 * s2 + 6], st[8 * s2 + 7]);
;                 const bf16x8 pf = __builtin_bit_cast(bf16x8, pw);
;                 LAS const unsigned char* vp = lds + LDS_VOFF + (32 * wave + 32 * j + 16 * s2 + 4 * h + q) * VP + 32 * blk + 8 * p;
; #pragma unroll
;                 for (int dt = 0; dt < 2; ++dt) { const s16x4 lo = trrd(vp + dt * 64), hi = trrd(vp + 8 * VP + dt * 64);
;                     const bf16x8 vf = __builtin_shufflevector(lo, hi, 0, 1, 2, 3, 4, 5, 6, 7);
;                     o[dt] = __builtin_amdgcn_mfma_f32_32x32x16_bf16(vf, pf, o[dt], 0, 0, 0); } }
;             __builtin_amdgcn_sched_barrier(0);
;         }
	s_nop 0
	v_mfma_f32_32x32x16_bf16 v[32:47], v[48:51], v[52:55], v[32:47]
	v_add_f32_e32 v48, v235, v234
	v_add_f32_e32 v48, v236, v48
	v_add_f32_e32 v48, v237, v48
	v_add_f32_e32 v48, v60, v48
	v_add_f32_e32 v48, v61, v48
	v_add_f32_e32 v48, v62, v48
	v_add_f32_e32 v48, v63, v48
	s_waitcnt lgkmcnt(0)
	v_mfma_f32_32x32x16_bf16 v[16:31], v[56:59], v[52:55], v[16:31]
	v_add_f32_e32 v238, v238, v48
	ds_read_b128 v[226:229], v205
	ds_read_b128 v[230:233], v205 offset:32
	v_add_f32_e32 v239, 0x42000000, v225
	v_add_f32_e32 v240, 0x42040000, v225
	v_cmp_nge_f32_e32 vcc, v239, v169
	s_waitcnt lgkmcnt(1)
	v_mfma_f32_32x32x16_bf16 v[48:63], v[226:229], v[136:139], v[0:15]
	ds_read_b128 v[226:229], v205 offset:64
	ds_read_b128 v[234:237], v205 offset:96
	v_cmp_nle_f32_e64 s[6:7], v239, v223
	v_add_f32_e32 v241, 0x42080000, v225
	v_cmp_nge_f32_e64 s[8:9], v240, v169
	v_cmp_nle_f32_e64 s[10:11], v240, v223
	s_or_b64 vcc, vcc, s[6:7]
	v_add_f32_e32 v242, 0x420c0000, v225
	s_waitcnt lgkmcnt(2)
	v_mfma_f32_32x32x16_bf16 v[48:63], v[230:233], v[132:135], v[48:63]
	v_cmp_nge_f32_e64 s[12:13], v241, v169
	v_cmp_nle_f32_e64 s[14:15], v241, v223
	v_add_f32_e32 v230, 0x42200000, v225
	v_cmp_nge_f32_e64 s[16:17], v242, v169
	v_cmp_nle_f32_e64 s[20:21], v242, v223
	v_add_f32_e32 v231, 0x42240000, v225
	v_cmp_nge_f32_e64 s[22:23], v230, v169
	s_waitcnt lgkmcnt(1)
	v_mfma_f32_32x32x16_bf16 v[48:63], v[226:229], v[128:131], v[48:63]
	v_cmp_nle_f32_e64 s[24:25], v230, v223
	v_cmp_nge_f32_e64 s[26:27], v231, v169
	v_cmp_nle_f32_e64 s[28:29], v231, v223
	s_waitcnt lgkmcnt(0)
	v_mfma_f32_32x32x16_bf16 v[48:63], v[234:237], v[140:143], v[48:63]
	s_nop 11
	v_fma_f32 v48, v224, |v239|, v48
	v_fma_f32 v49, v224, |v240|, v49
	v_cndmask_b32_e32 v48, v48, v221, vcc
	s_or_b64 vcc, s[8:9], s[10:11]
	v_fma_f32 v50, v224, |v241|, v50
	v_cndmask_b32_e32 v49, v49, v221, vcc
	s_or_b64 vcc, s[12:13], s[14:15]
	v_fma_f32 v51, v224, |v242|, v51
	v_cndmask_b32_e32 v50, v50, v221, vcc
	s_or_b64 vcc, s[16:17], s[20:21]
	v_fma_f32 v52, v224, |v230|, v52
	v_cndmask_b32_e32 v51, v51, v221, vcc
	s_or_b64 vcc, s[22:23], s[24:25]
	v_fma_f32 v53, v224, |v231|, v53
	v_cndmask_b32_e32 v52, v52, v221, vcc
	s_or_b64 vcc, s[26:27], s[28:29]
	v_exp_f32_e32 v227, v49
	v_cndmask_b32_e32 v49, v53, v221, vcc
	v_exp_f32_e32 v231, v49
	v_add_f32_e32 v49, 0x42280000, v225
	v_cmp_nge_f32_e32 vcc, v49, v169
	v_cmp_nle_f32_e64 s[6:7], v49, v223
	v_exp_f32_e32 v228, v50
	v_fma_f32 v50, v224, |v49|, v54
	s_or_b64 vcc, vcc, s[6:7]
	v_cndmask_b32_e32 v49, v50, v221, vcc
	v_exp_f32_e32 v226, v48
	v_exp_f32_e32 v232, v49
	v_add_f32_e32 v49, 0x422c0000, v225
	v_cmp_nge_f32_e32 vcc, v49, v169
	v_cmp_nle_f32_e64 s[6:7], v49, v223
	v_fma_f32 v50, v224, |v49|, v55
	s_or_b64 vcc, vcc, s[6:7]
	v_exp_f32_e32 v229, v51
	v_cndmask_b32_e32 v49, v50, v221, vcc
	v_exp_f32_e32 v230, v52
	v_add_f32_e32 v48, 0, v226
	v_exp_f32_e32 v55, v49
	v_add_f32_e32 v49, 0x42400000, v225
	v_add_f32_e32 v48, v227, v48
	v_cmp_nge_f32_e32 vcc, v49, v169
	v_cmp_nle_f32_e64 s[6:7], v49, v223
	v_add_f32_e32 v48, v228, v48
	v_fma_f32 v50, v224, |v49|, v56
	s_or_b64 vcc, vcc, s[6:7]
	v_add_f32_e32 v48, v229, v48
	v_cndmask_b32_e32 v49, v50, v221, vcc
	v_add_f32_e32 v48, v230, v48
	v_exp_f32_e32 v233, v49
	v_add_f32_e32 v48, v231, v48
	v_add_f32_e32 v48, v232, v48
	v_add_f32_e32 v48, v55, v48
	v_add_f32_e32 v234, v233, v48
	v_add_f32_e32 v48, 0x42440000, v225
	v_cmp_nge_f32_e32 vcc, v48, v169
	v_cmp_nle_f32_e64 s[6:7], v48, v223
	v_fma_f32 v49, v224, |v48|, v57
	s_or_b64 vcc, vcc, s[6:7]
	v_cndmask_b32_e32 v48, v49, v221, vcc
	v_exp_f32_e32 v235, v48
	v_add_f32_e32 v48, 0x42480000, v225
	v_cmp_nge_f32_e32 vcc, v48, v169
	v_cmp_nle_f32_e64 s[6:7], v48, v223
	v_fma_f32 v49, v224, |v48|, v58
	s_or_b64 vcc, vcc, s[6:7]
	v_cndmask_b32_e32 v48, v49, v221, vcc
	v_exp_f32_e32 v236, v48
	v_add_f32_e32 v48, 0x424c0000, v225
	v_cmp_nge_f32_e32 vcc, v48, v169
	v_cmp_nle_f32_e64 s[6:7], v48, v223
	v_fma_f32 v49, v224, |v48|, v59
	s_or_b64 vcc, vcc, s[6:7]
	v_cndmask_b32_e32 v48, v49, v221, vcc
	v_exp_f32_e32 v237, v48
	v_add_f32_e32 v48, 0x42600000, v225
	v_cmp_nge_f32_e32 vcc, v48, v169
	v_cmp_nle_f32_e64 s[6:7], v48, v223
	v_fma_f32 v49, v224, |v48|, v60
	s_or_b64 vcc, vcc, s[6:7]
	v_cndmask_b32_e32 v48, v49, v221, vcc
	v_exp_f32_e32 v60, v48
	v_add_f32_e32 v48, 0x42640000, v225
	v_cmp_nge_f32_e32 vcc, v48, v169
	v_cmp_nle_f32_e64 s[6:7], v48, v223
	v_fma_f32 v49, v224, |v48|, v61
	s_or_b64 vcc, vcc, s[6:7]
	v_cndmask_b32_e32 v48, v49, v221, vcc
	v_exp_f32_e32 v61, v48
	v_add_f32_e32 v48, 0x42680000, v225
	v_cmp_nge_f32_e32 vcc, v48, v169
	v_cmp_nle_f32_e64 s[6:7], v48, v223
	v_fma_f32 v49, v224, |v48|, v62
	s_or_b64 vcc, vcc, s[6:7]
	v_cndmask_b32_e32 v52, v49, v221, vcc
	ds_read_b64_tr_b16 v[48:49], v206 offset:55296
	ds_read_b64_tr_b16 v[50:51], v206 offset:56832
	ds_read_b64_tr_b16 v[58:59], v206 offset:56896
	ds_read_b64_tr_b16 v[56:57], v206 offset:55360
	v_exp_f32_e32 v62, v52
	v_add_f32_e32 v239, 0x426c0000, v225
	v_cvt_pk_bf16_f32 v52, v226, v227
	v_cvt_pk_bf16_f32 v53, v228, v229
	v_cvt_pk_bf16_f32 v54, v230, v231
	v_cvt_pk_bf16_f32 v55, v232, v55
	v_cmp_nge_f32_e32 vcc, v239, v169
	v_cmp_nle_f32_e64 s[6:7], v239, v223
	s_waitcnt lgkmcnt(2)
	v_mfma_f32_32x32x16_bf16 v[32:47], v[48:51], v[52:55], v[32:47]
	v_fma_f32 v48, v224, |v239|, v63
	s_or_b64 vcc, vcc, s[6:7]
	v_cndmask_b32_e32 v63, v48, v221, vcc
	ds_read_b64_tr_b16 v[48:49], v206 offset:58368
	ds_read_b64_tr_b16 v[50:51], v206 offset:59904
	v_exp_f32_e32 v63, v63
	s_waitcnt lgkmcnt(2)
	v_mfma_f32_32x32x16_bf16 v[16:31], v[56:59], v[52:55], v[16:31]
	ds_read_b64_tr_b16 v[58:59], v206 offset:59968
	ds_read_b64_tr_b16 v[56:57], v206 offset:58432
	v_cvt_pk_bf16_f32 v52, v233, v235
	v_cvt_pk_bf16_f32 v53, v236, v237
	v_cvt_pk_bf16_f32 v54, v60, v61
	v_cvt_pk_bf16_f32 v55, v62, v63
	s_waitcnt lgkmcnt(2)
	s_nop 0
	v_mfma_f32_32x32x16_bf16 v[32:47], v[48:51], v[52:55], v[32:47]
	v_add_f32_e32 v48, v235, v234
	v_add_f32_e32 v48, v236, v48
	v_add_f32_e32 v48, v237, v48
	v_add_f32_e32 v48, v60, v48
	v_add_f32_e32 v48, v61, v48
	v_add_f32_e32 v48, v62, v48
	v_add_f32_e32 v48, v63, v48
	s_waitcnt lgkmcnt(0)
	v_mfma_f32_32x32x16_bf16 v[16:31], v[56:59], v[52:55], v[16:31]
	v_add_f32_e32 v60, v238, v48
; #define LAS __attribute__((address_space(3)))
; __device__ __forceinline__ unsigned pk2(float lo, float hi) { f32x2_t v = {lo, hi}; bf16x2_t b = __builtin_convertvector(v, bf16x2_t); return __builtin_bit_cast(unsigned, b); }
; __device__ __forceinline__ s16x4 trrd(LAS const unsigned char* p) { return __builtin_bit_cast(s16x4, __builtin_amdgcn_ds_read_tr16_b64_v4i16((LAS v4i16_t*)p)); }
; #define ATTN_QLOAD(W) do { const bf16_t* qr_ = Qb + ((size_t)((W).b * 24 + (W).hd) * SEQ + (size_t)((W).r * (W).L + (W).i0 + 32 * wave + l31)) * 64; \
;         _Pragma("unroll") for (int ks_ = 0; ks_ < 4; ++ks_) qv[ks_] = *(const u32x4*)(qr_ + 16 * ks_ + 8 * h); } while (0)
; template <bool FUSED> __device__ __forceinline__ void attn_phase(const Args& a, LAS unsigned char* lds, int tid, int lane, int wave) {
;     ...
;         for (int j = 0; j < 5; ++j) {
;             f32x16 st;
; #pragma unroll
;             for (int i = 0; i < 16; ++i) st[i] = -mb;
;             LAS const unsigned char* kp = lds + (32 * wave + 32 * j + l31) * KP + 16 * h;
; #pragma unroll
;             for (int ks = 0; ks < 4; ++ks) { const bf16x8 kf = *(LAS const bf16x8*)(kp + 32 * ks); st = __builtin_amdgcn_mfma_f32_32x32x16_bf16(kf, qf[ks], st, 0, 0, 0); }
;             sum += attn_tile_exp(st, j, tlf, bsl, rlo, rhi);
; #pragma unroll
;             for (int s2 = 0; s2 < 2; ++s2) { u32x4 pw; pw.x = pk2(st[8 * s2 + 0], st[8 * s2 + 1]); pw.y = pk2(st[8 * s2 + 2], st[8 * s2 + 3]); pw.z = pk2(st[8 * s2 + 4], st[8 * s2 + 5]); pw.w = pk2(st[8 * s2 + 6], st[8 * s2 + 7]);
;                 const bf16x8 pf = __builtin_bit_cast(bf16x8, pw);
;                 LAS const unsigned char* vp = lds + LDS_VOFF + (32 * wave + 32 * j + 16 * s2 + 4 * h + q) * VP + 32 * blk + 8 * p;
; #pragma unroll
;                 for (int dt = 0; dt < 2; ++dt) { const s16x4 lo = trrd(vp + dt * 64), hi = trrd(vp + 8 * VP + dt * 64);
;                     const bf16x8 vf = __builtin_shufflevector(lo, hi, 0, 1, 2, 3, 4, 5, 6, 7);
;                     o[dt] = __builtin_amdgcn_mfma_f32_32x32x16_bf16(vf, pf, o[dt], 0, 0, 0); } }
;             __builtin_amdgcn_sched_barrier(0);
;         }
;         sum += __shfl_xor(sum, 32);
;         if (un < NU) { const AUnit wq = attn_decode(un, HD0, NH); ATTN_QLOAD(wq); }
.Lattn1_t4:
	ds_read_b128 v[48:51], v207
	ds_read_b128 v[52:55], v207 offset:32
	v_add_f32_e32 v61, 0x42800000, v225
	v_add_f32_e32 v62, 0x42820000, v225
	v_cmp_nge_f32_e32 vcc, v61, v169
	s_waitcnt lgkmcnt(1)
	v_mfma_f32_32x32x16_bf16 v[0:15], v[48:51], v[136:139], v[0:15]
	ds_read_b128 v[48:51], v207 offset:64
	ds_read_b128 v[56:59], v207 offset:96
	v_cmp_nle_f32_e64 s[6:7], v61, v223
	v_add_f32_e32 v63, 0x42840000, v225
	v_cmp_nge_f32_e64 s[8:9], v62, v169
	v_cmp_nle_f32_e64 s[10:11], v62, v223
	s_or_b64 vcc, vcc, s[6:7]
	v_add_f32_e32 v136, 0x42860000, v225
	s_waitcnt lgkmcnt(2)
	v_mfma_f32_32x32x16_bf16 v[0:15], v[52:55], v[132:135], v[0:15]
	v_cmp_nge_f32_e64 s[12:13], v63, v169
	v_cmp_nle_f32_e64 s[14:15], v63, v223
	v_add_f32_e32 v52, 0x42900000, v225
	v_cmp_nge_f32_e64 s[16:17], v136, v169
	v_cmp_nle_f32_e64 s[20:21], v136, v223
	v_add_f32_e32 v53, 0x42920000, v225
	v_cmp_nge_f32_e64 s[22:23], v52, v169
	s_waitcnt lgkmcnt(1)
	v_mfma_f32_32x32x16_bf16 v[0:15], v[48:51], v[128:131], v[0:15]
	v_cmp_nle_f32_e64 s[24:25], v52, v223
	v_cmp_nge_f32_e64 s[26:27], v53, v169
	v_cmp_nle_f32_e64 s[28:29], v53, v223
	s_waitcnt lgkmcnt(0)
	v_mfma_f32_32x32x16_bf16 v[0:15], v[56:59], v[140:143], v[0:15]
	s_nop 11
	v_fma_f32 v0, v224, |v61|, v0
	v_fma_f32 v1, v224, |v62|, v1
	v_cndmask_b32_e32 v0, v0, v221, vcc
	s_or_b64 vcc, s[8:9], s[10:11]
	v_fma_f32 v2, v224, |v63|, v2
	v_cndmask_b32_e32 v1, v1, v221, vcc
	s_or_b64 vcc, s[12:13], s[14:15]
	v_fma_f32 v3, v224, |v136|, v3
	v_cndmask_b32_e32 v2, v2, v221, vcc
	s_or_b64 vcc, s[16:17], s[20:21]
	v_fma_f32 v4, v224, |v52|, v4
	v_cndmask_b32_e32 v3, v3, v221, vcc
	s_or_b64 vcc, s[22:23], s[24:25]
	v_fma_f32 v5, v224, |v53|, v5
	v_cndmask_b32_e32 v4, v4, v221, vcc
	s_or_b64 vcc, s[26:27], s[28:29]
	v_exp_f32_e32 v49, v1
	v_cndmask_b32_e32 v1, v5, v221, vcc
	v_exp_f32_e32 v53, v1
	v_add_f32_e32 v1, 0x42940000, v225
	v_cmp_nge_f32_e32 vcc, v1, v169
	v_cmp_nle_f32_e64 s[6:7], v1, v223
	v_exp_f32_e32 v50, v2
	v_fma_f32 v2, v224, |v1|, v6
	s_or_b64 vcc, vcc, s[6:7]
	v_cndmask_b32_e32 v1, v2, v221, vcc
	v_exp_f32_e32 v48, v0
	v_exp_f32_e32 v54, v1
	v_add_f32_e32 v1, 0x42960000, v225
	v_cmp_nge_f32_e32 vcc, v1, v169
	v_cmp_nle_f32_e64 s[6:7], v1, v223
	v_fma_f32 v2, v224, |v1|, v7
	s_or_b64 vcc, vcc, s[6:7]
	v_exp_f32_e32 v51, v3
	v_cndmask_b32_e32 v1, v2, v221, vcc
	v_exp_f32_e32 v52, v4
	v_add_f32_e32 v0, 0, v48
	v_exp_f32_e32 v7, v1
	v_add_f32_e32 v1, 0x42a00000, v225
	v_add_f32_e32 v0, v49, v0
	v_cmp_nge_f32_e32 vcc, v1, v169
	v_cmp_nle_f32_e64 s[6:7], v1, v223
	v_add_f32_e32 v0, v50, v0
	v_fma_f32 v2, v224, |v1|, v8
	s_or_b64 vcc, vcc, s[6:7]
	v_add_f32_e32 v0, v51, v0
	v_cndmask_b32_e32 v1, v2, v221, vcc
	v_add_f32_e32 v0, v52, v0
	v_exp_f32_e32 v55, v1
	v_add_f32_e32 v0, v53, v0
	v_add_f32_e32 v0, v54, v0
	v_add_f32_e32 v0, v7, v0
	v_add_f32_e32 v56, v55, v0
	v_add_f32_e32 v0, 0x42a20000, v225
	v_cmp_nge_f32_e32 vcc, v0, v169
	v_cmp_nle_f32_e64 s[6:7], v0, v223
	v_fma_f32 v1, v224, |v0|, v9
	s_or_b64 vcc, vcc, s[6:7]
	v_cndmask_b32_e32 v0, v1, v221, vcc
	v_exp_f32_e32 v57, v0
	v_add_f32_e32 v0, 0x42a40000, v225
	v_cmp_nge_f32_e32 vcc, v0, v169
	v_cmp_nle_f32_e64 s[6:7], v0, v223
	v_fma_f32 v1, v224, |v0|, v10
	s_or_b64 vcc, vcc, s[6:7]
	v_cndmask_b32_e32 v0, v1, v221, vcc
	v_exp_f32_e32 v58, v0
	v_add_f32_e32 v0, 0x42a60000, v225
	v_cmp_nge_f32_e32 vcc, v0, v169
	v_cmp_nle_f32_e64 s[6:7], v0, v223
	v_fma_f32 v1, v224, |v0|, v11
	s_or_b64 vcc, vcc, s[6:7]
	v_cndmask_b32_e32 v0, v1, v221, vcc
	v_exp_f32_e32 v59, v0
	v_add_f32_e32 v0, 0x42b00000, v225
	v_cmp_nge_f32_e32 vcc, v0, v169
	v_cmp_nle_f32_e64 s[6:7], v0, v223
	v_fma_f32 v1, v224, |v0|, v12
	s_or_b64 vcc, vcc, s[6:7]
	v_cndmask_b32_e32 v0, v1, v221, vcc
	v_exp_f32_e32 v12, v0
	v_add_f32_e32 v0, 0x42b20000, v225
	v_cmp_nge_f32_e32 vcc, v0, v169
	v_cmp_nle_f32_e64 s[6:7], v0, v223
	v_fma_f32 v1, v224, |v0|, v13
	s_or_b64 vcc, vcc, s[6:7]
	v_cndmask_b32_e32 v0, v1, v221, vcc
	v_exp_f32_e32 v13, v0
	v_add_f32_e32 v0, 0x42b40000, v225
	v_cmp_nge_f32_e32 vcc, v0, v169
	v_cmp_nle_f32_e64 s[6:7], v0, v223
	v_fma_f32 v1, v224, |v0|, v14
	s_or_b64 vcc, vcc, s[6:7]
	v_cndmask_b32_e32 v4, v1, v221, vcc
	ds_read_b64_tr_b16 v[0:1], v208 offset:55296
	ds_read_b64_tr_b16 v[2:3], v208 offset:56832
	ds_read_b64_tr_b16 v[10:11], v208 offset:56896
	ds_read_b64_tr_b16 v[8:9], v208 offset:55360
	v_exp_f32_e32 v14, v4
	v_add_f32_e32 v61, 0x42b60000, v225
	v_cvt_pk_bf16_f32 v4, v48, v49
	v_cvt_pk_bf16_f32 v5, v50, v51
	v_cvt_pk_bf16_f32 v6, v52, v53
	v_cvt_pk_bf16_f32 v7, v54, v7
	v_cmp_nge_f32_e32 vcc, v61, v169
	v_cmp_nle_f32_e64 s[6:7], v61, v223
	s_waitcnt lgkmcnt(2)
	v_mfma_f32_32x32x16_bf16 v[32:47], v[0:3], v[4:7], v[32:47]
	v_fma_f32 v0, v224, |v61|, v15
	s_or_b64 vcc, vcc, s[6:7]
	v_cndmask_b32_e32 v15, v0, v221, vcc
	ds_read_b64_tr_b16 v[0:1], v208 offset:58368
	ds_read_b64_tr_b16 v[2:3], v208 offset:59904
	v_exp_f32_e32 v15, v15
	s_waitcnt lgkmcnt(2)
	v_mfma_f32_32x32x16_bf16 v[16:31], v[8:11], v[4:7], v[16:31]
	ds_read_b64_tr_b16 v[10:11], v208 offset:59968
	ds_read_b64_tr_b16 v[8:9], v208 offset:58432
	v_cvt_pk_bf16_f32 v4, v55, v57
	v_cvt_pk_bf16_f32 v5, v58, v59
	v_cvt_pk_bf16_f32 v6, v12, v13
	v_cvt_pk_bf16_f32 v7, v14, v15
	s_waitcnt lgkmcnt(2)
	s_nop 0
	v_mfma_f32_32x32x16_bf16 v[32:47], v[0:3], v[4:7], v[32:47]
	v_add_f32_e32 v0, v57, v56
	v_add_f32_e32 v0, v58, v0
	v_add_f32_e32 v0, v59, v0
	v_add_f32_e32 v0, v12, v0
	v_add_f32_e32 v0, v13, v0
	v_add_f32_e32 v0, v14, v0
	v_add_f32_e32 v0, v15, v0
	s_waitcnt lgkmcnt(0)
	v_mfma_f32_32x32x16_bf16 v[16:31], v[8:11], v[4:7], v[16:31]
	v_add_f32_e32 v0, v60, v0
	ds_bpermute_b32 v1, v153, v0
	s_andn2_b64 vcc, exec, s[72:73]
	s_cbranch_vccnz .LBB0_284
	s_ashr_i32 s7, s69, 5
	s_lshr_b32 s8, s7, 28
	s_add_i32 s8, s7, s8
	s_and_b32 s8, s8, -16
	s_sub_i32 s7, s7, s8
	s_add_i32 s7, s7, 8
	s_ashr_i32 s8, s69, 31
	s_ashr_i32 s9, s7, 2
	s_lshr_b32 s8, s8, 23
	s_and_b32 s9, s9, -2
	s_add_i32 s8, s69, s8
	s_lshr_b32 s10, 32, s9
	s_and_b32 s6, s69, 31
	s_ashr_i32 s8, s8, 9
	s_lshr_b32 s11, 0x2000, s9
	s_sub_i32 s9, 5, s9
	s_add_i32 s10, s10, -1
	s_lshr_b32 s9, s6, s9
	s_and_b32 s6, s10, s6
	s_mul_i32 s8, s8, 24
	s_lshl_b32 s10, s6, 8
	s_add_i32 s6, s7, s8
	s_mul_i32 s9, s9, s11
	s_ashr_i32 s7, s6, 31
	s_add_i32 s10, s10, s9
	v_add_u32_e32 v2, s10, v145
	s_lshl_b64 s[6:7], s[6:7], 20
	v_ashrrev_i32_e32 v3, 31, v2
	s_add_u32 s6, s40, s6
	s_addc_u32 s7, s41, s7
	v_lshlrev_b64 v[2:3], 7, v[2:3]
	v_lshl_add_u64 v[2:3], s[6:7], 0, v[2:3]
	v_lshl_add_u64 v[2:3], v[148:149], 1, v[2:3]
	global_load_dwordx4 v[88:91], v[2:3], off
	global_load_dwordx4 v[92:95], v[2:3], off offset:32
	global_load_dwordx4 v[100:103], v[2:3], off offset:64
	global_load_dwordx4 v[108:111], v[2:3], off offset:96

; #define LAS __attribute__((address_space(3)))
; template <bool FUSED> __device__ __forceinline__ void attn_phase(const Args& a, LAS unsigned char* lds, int tid, int lane, int wave) {
;     ...
;             const float rq = 0.125f * LOG2E * __builtin_amdgcn_rsqf(ss * (1.f / 64.f) + 1e-6f);
; #pragma unroll
;             for (int ks = 0; ks < 4; ++ks) { const f32x4 g0 = *(const f32x4*)(a.qw + hd * 64 + 16 * ks + 8 * h), g1 = *(const f32x4*)(a.qw + hd * 64 + 16 * ks + 8 * h + 4); u32x4 wv;
;                 wv.x = pk2(bflo(qv[ks].x) * rq * g0.x, bfhi(qv[ks].x) * rq * g0.y); wv.y = pk2(bflo(qv[ks].y) * rq * g0.z, bfhi(qv[ks].y) * rq * g0.w);
;                 wv.z = pk2(bflo(qv[ks].z) * rq * g1.x, bfhi(qv[ks].z) * rq * g1.y); wv.w = pk2(bflo(qv[ks].w) * rq * g1.z, bfhi(qv[ks].w) * rq * g1.w);
;                 qf[ks] = __builtin_bit_cast(bf16x8, wv); }
;     ...
;         const float bsl = __builtin_amdgcn_exp2f(-(float)(slot + 1)) * (float)w.dil * LOG2E;
;         int tl = 4 * h - l31; asm volatile("" : "+v"(tl));
;         const float tlf = (float)tl;
;         const int lo_i = -iq > -64 ? -iq : -64, hi_i = (L - 1 - iq) < 64 ? (L - 1 - iq) : 64;
;         const float rlo = (float)lo_i, rhi = (float)hi_i;
;         const int wq0 = i0 + 32 * wave;
;         const bool edge = (wq0 < 64) || (wq0 + 32 > L - 64);
;         float sum = 0.f;
;         f32x16 o[2]; o[0] = f32x16{}; o[1] = f32x16{};
; #pragma unroll
;         for (int j = 0; j < 5; ++j) {
;             f32x16 st;
; #pragma unroll
;             for (int i = 0; i < 16; ++i) st[i] = -mb;
;             LAS const unsigned char* kp = lds + (32 * wave + 32 * j + l31) * KP + 16 * h;
; #pragma unroll
;             for (int ks = 0; ks < 4; ++ks) { const bf16x8 kf = *(LAS const bf16x8*)(kp + 32 * ks); st = __builtin_amdgcn_mfma_f32_32x32x16_bf16(kf, qf[ks], st, 0, 0, 0); }
;             sum += attn_tile_exp(st, j, tlf, bsl, rlo, rhi);
; #pragma unroll
;             for (int s2 = 0; s2 < 2; ++s2) { u32x4 pw; pw.x = pk2(st[8 * s2 + 0], st[8 * s2 + 1]); pw.y = pk2(st[8 * s2 + 2], st[8 * s2 + 3]); pw.z = pk2(st[8 * s2 + 4], st[8 * s2 + 5]); pw.w = pk2(st[8 * s2 + 6], st[8 * s2 + 7]);
;                 const bf16x8 pf = __builtin_bit_cast(bf16x8, pw);
;                 LAS const unsigned char* vp = lds + LDS_VOFF + (32 * wave + 32 * j + 16 * s2 + 4 * h + q) * VP + 32 * blk + 8 * p;
; #pragma unroll
.Lattn2_join:
	v_xor_b32_e32 v32, 0x80000000, v229
	v_pk_mul_f32 v[0:1], v[0:1], v[2:3]
	v_mov_b32_e32 v33, v32
	v_mov_b32_e32 v34, v32
	v_mov_b32_e32 v35, v32
	v_mov_b32_e32 v36, v32
	v_mov_b32_e32 v37, v32
	v_mov_b32_e32 v38, v32
	v_mov_b32_e32 v39, v32
	v_mov_b32_e32 v40, v32
	v_mov_b32_e32 v41, v32
	v_mov_b32_e32 v42, v32
	v_mov_b32_e32 v43, v32
	v_mov_b32_e32 v44, v32
	v_mov_b32_e32 v45, v32
	v_mov_b32_e32 v46, v32
	v_mov_b32_e32 v47, v32
	v_cvt_pk_bf16_f32 v141, v0, v1
	s_and_b32 s8, s8, 31
	s_waitcnt lgkmcnt(0)
	v_mfma_f32_32x32x16_bf16 v[0:15], v[20:23], v[136:139], v[32:47]
	v_mul_f32_e64 v20, v60, v50
	v_mul_f32_e64 v21, v60, v51
	v_mul_f32_e64 v16, v20, v16
	v_mul_f32_e64 v17, v21, v17
	ds_read_b128 v[20:23], v206 offset:64
	v_cvt_pk_bf16_f32 v142, v16, v17
	v_cvt_f32_ubyte0_e32 v16, s6
	v_exp_f32_e64 v29, -v16
	v_pk_mul_f32 v[16:17], v[60:61], v[48:49] op_sel_hi:[0,1]
	v_mfma_f32_32x32x16_bf16 v[0:15], v[24:27], v[132:135], v[0:15]
	v_mul_f32_e64 v16, v16, v18
	v_mul_f32_e64 v17, v17, v19
	s_lshl_b32 s66, s8, 8
	v_cvt_pk_bf16_f32 v143, v16, v17
	ds_read_b128 v[16:19], v206 offset:96
	s_add_i32 s66, s66, s48
	s_lshl_b32 s9, 1, s7
	s_lshr_b32 s7, 0x2000, s7
	s_waitcnt lgkmcnt(1)
	v_mfma_f32_32x32x16_bf16 v[0:15], v[20:23], v[128:131], v[0:15]
	v_or_b32_e32 v62, s66, v145
	v_sub_u32_e32 v20, 0, v62
	v_xad_u32 v21, v62, -1, s7
	v_cvt_f32_u32_e32 v24, s9
	v_cvt_f32_i32_e32 v171, v28
	v_max_i32_e32 v20, 0xffffffc0, v20
	v_min_i32_e32 v21, 64, v21
	s_waitcnt lgkmcnt(0)
	v_mfma_f32_32x32x16_bf16 v[0:15], v[16:19], v[140:143], v[0:15]
	v_cvt_f32_i32_e32 v168, v20
	v_cvt_f32_i32_e32 v169, v21
	v_mul_f32_e32 v24, v29, v24
	v_add_f32_e32 v16, 0xc2800000, v171
	v_mul_f32_e32 v170, 0xbfb8aa3b, v24
	v_cmp_nge_f32_e32 vcc, v16, v168
	v_cmp_nle_f32_e64 s[6:7], v16, v169
	s_nop 4
	v_fma_f32 v0, v170, |v16|, v0
	s_or_b64 vcc, vcc, s[6:7]
	v_add_f32_e32 v17, 0xc27c0000, v171
	v_cndmask_b32_e32 v0, v0, v228, vcc
	v_cmp_nge_f32_e32 vcc, v17, v168
	v_cmp_nle_f32_e64 s[6:7], v17, v169
	v_fma_f32 v1, v170, |v17|, v1
	s_or_b64 vcc, vcc, s[6:7]
	v_cndmask_b32_e32 v1, v1, v228, vcc
	v_exp_f32_e32 v17, v1
	v_add_f32_e32 v1, 0xc2780000, v171
	v_cmp_nge_f32_e32 vcc, v1, v168
	v_cmp_nle_f32_e64 s[6:7], v1, v169
	v_fma_f32 v2, v170, |v1|, v2
	s_or_b64 vcc, vcc, s[6:7]
	v_cndmask_b32_e32 v1, v2, v228, vcc
	v_exp_f32_e32 v18, v1
	v_add_f32_e32 v1, 0xc2740000, v171
	v_cmp_nge_f32_e32 vcc, v1, v168
	v_cmp_nle_f32_e64 s[6:7], v1, v169
	v_fma_f32 v2, v170, |v1|, v3
	s_or_b64 vcc, vcc, s[6:7]
	v_cndmask_b32_e32 v1, v2, v228, vcc
	v_exp_f32_e32 v19, v1
	v_add_f32_e32 v1, 0xc2600000, v171
	v_cmp_nge_f32_e32 vcc, v1, v168
	v_cmp_nle_f32_e64 s[6:7], v1, v169
	v_fma_f32 v2, v170, |v1|, v4
	s_or_b64 vcc, vcc, s[6:7]
	v_cndmask_b32_e32 v1, v2, v228, vcc
	v_exp_f32_e32 v20, v1
	v_add_f32_e32 v1, 0xc25c0000, v171
	v_cmp_nge_f32_e32 vcc, v1, v168
	v_cmp_nle_f32_e64 s[6:7], v1, v169
	v_fma_f32 v2, v170, |v1|, v5
	s_or_b64 vcc, vcc, s[6:7]
	v_cndmask_b32_e32 v1, v2, v228, vcc
	v_exp_f32_e32 v21, v1
	v_add_f32_e32 v1, 0xc2580000, v171
	v_cmp_nge_f32_e32 vcc, v1, v168
	v_cmp_nle_f32_e64 s[6:7], v1, v169
	v_fma_f32 v2, v170, |v1|, v6
	s_or_b64 vcc, vcc, s[6:7]
	v_cndmask_b32_e32 v1, v2, v228, vcc
	v_exp_f32_e32 v16, v0
	v_exp_f32_e32 v22, v1
	v_add_f32_e32 v1, 0xc2540000, v171
	v_cmp_nge_f32_e32 vcc, v1, v168
	v_cmp_nle_f32_e64 s[6:7], v1, v169
	v_fma_f32 v2, v170, |v1|, v7
	s_or_b64 vcc, vcc, s[6:7]
	v_cndmask_b32_e32 v1, v2, v228, vcc
	v_add_f32_e32 v0, 0, v16
	v_exp_f32_e32 v7, v1
	v_add_f32_e32 v1, 0xc2400000, v171
	v_add_f32_e32 v0, v17, v0
	v_cmp_nge_f32_e32 vcc, v1, v168
	v_cmp_nle_f32_e64 s[6:7], v1, v169
	v_add_f32_e32 v0, v18, v0
	v_fma_f32 v2, v170, |v1|, v8
	s_or_b64 vcc, vcc, s[6:7]
	v_add_f32_e32 v0, v19, v0
	v_cndmask_b32_e32 v1, v2, v228, vcc
	v_add_f32_e32 v0, v20, v0
	v_exp_f32_e32 v52, v1
	v_add_f32_e32 v0, v21, v0
	v_add_f32_e32 v0, v22, v0
	v_add_f32_e32 v0, v7, v0
	v_add_f32_e32 v60, v52, v0
	v_add_f32_e32 v0, 0xc23c0000, v171
	v_cmp_nge_f32_e32 vcc, v0, v168
	v_cmp_nle_f32_e64 s[6:7], v0, v169
	v_fma_f32 v1, v170, |v0|, v9
	s_or_b64 vcc, vcc, s[6:7]
	v_cndmask_b32_e32 v0, v1, v228, vcc
	v_exp_f32_e32 v61, v0
	v_add_f32_e32 v0, 0xc2380000, v171
	v_cmp_nge_f32_e32 vcc, v0, v168
	v_cmp_nle_f32_e64 s[6:7], v0, v169
	v_fma_f32 v1, v170, |v0|, v10
	s_or_b64 vcc, vcc, s[6:7]
	v_cndmask_b32_e32 v0, v1, v228, vcc
	v_exp_f32_e32 v62, v0
	v_add_f32_e32 v0, 0xc2340000, v171
	v_cmp_nge_f32_e32 vcc, v0, v168
	v_cmp_nle_f32_e64 s[6:7], v0, v169
	v_fma_f32 v1, v170, |v0|, v11
	s_or_b64 vcc, vcc, s[6:7]
	v_cndmask_b32_e32 v0, v1, v228, vcc
	v_exp_f32_e32 v63, v0
	v_add_f32_e32 v0, 0xc2200000, v171
	v_cmp_nge_f32_e32 vcc, v0, v168
	v_cmp_nle_f32_e64 s[6:7], v0, v169
	v_fma_f32 v1, v170, |v0|, v12
	s_or_b64 vcc, vcc, s[6:7]
	v_cndmask_b32_e32 v0, v1, v228, vcc
	v_exp_f32_e32 v172, v0
	v_add_f32_e32 v0, 0xc21c0000, v171
	v_cmp_nge_f32_e32 vcc, v0, v168
	v_cmp_nle_f32_e64 s[6:7], v0, v169
	v_fma_f32 v1, v170, |v0|, v13
	s_or_b64 vcc, vcc, s[6:7]
	v_cndmask_b32_e32 v0, v1, v228, vcc
	v_exp_f32_e32 v173, v0
	v_add_f32_e32 v0, 0xc2180000, v171
	v_cmp_nge_f32_e32 vcc, v0, v168
	v_cmp_nle_f32_e64 s[6:7], v0, v169
	v_fma_f32 v1, v170, |v0|, v14
	s_or_b64 vcc, vcc, s[6:7]
	v_cndmask_b32_e32 v4, v1, v228, vcc
	ds_read_b64_tr_b16 v[0:1], v207 offset:55296
	ds_read_b64_tr_b16 v[2:3], v207 offset:56832
	ds_read_b64_tr_b16 v[10:11], v207 offset:56896
	ds_read_b64_tr_b16 v[8:9], v207 offset:55360
	v_add_f32_e32 v12, 0xc2140000, v171
	v_exp_f32_e32 v174, v4
	v_cvt_pk_bf16_f32 v4, v16, v17
	v_cvt_pk_bf16_f32 v5, v18, v19
	v_cvt_pk_bf16_f32 v6, v20, v21
	v_cvt_pk_bf16_f32 v7, v22, v7
	v_cmp_nge_f32_e32 vcc, v12, v168
	v_cmp_nle_f32_e64 s[6:7], v12, v169
	s_waitcnt lgkmcnt(2)
	v_mfma_f32_32x32x16_bf16 v[16:31], v[0:3], v[4:7], 0
	v_fma_f32 v0, v170, |v12|, v15
	s_or_b64 vcc, vcc, s[6:7]
	v_cndmask_b32_e32 v53, v0, v228, vcc
	ds_read_b64_tr_b16 v[48:49], v207 offset:58368
	ds_read_b64_tr_b16 v[50:51], v207 offset:59904
	v_exp_f32_e32 v175, v53
	ds_read_b64_tr_b16 v[58:59], v207 offset:59968
	ds_read_b64_tr_b16 v[56:57], v207 offset:58432
	v_cvt_pk_bf16_f32 v52, v52, v61
	s_waitcnt lgkmcnt(4)
	v_mfma_f32_32x32x16_bf16 v[0:15], v[8:11], v[4:7], 0
	v_cvt_pk_bf16_f32 v53, v62, v63
	v_cvt_pk_bf16_f32 v54, v172, v173
	v_cvt_pk_bf16_f32 v55, v174, v175
	s_waitcnt lgkmcnt(2)
	s_nop 0
	v_mfma_f32_32x32x16_bf16 v[16:31], v[48:51], v[52:55], v[16:31]
	v_add_f32_e32 v48, v61, v60
	v_add_f32_e32 v48, v62, v48
	v_add_f32_e32 v48, v63, v48
	v_add_f32_e32 v48, v172, v48
	v_add_f32_e32 v48, v173, v48
	v_add_f32_e32 v48, v174, v48
	v_add_f32_e32 v48, v175, v48
	s_waitcnt lgkmcnt(0)
	v_mfma_f32_32x32x16_bf16 v[0:15], v[56:59], v[52:55], v[0:15]
	v_add_f32_e32 v238, 0, v48
	v_cmp_neq_f32_e32 vcc, 0xc2800000, v168
	s_mov_b64 s[6:7], vcc
	v_cmp_neq_f32_e32 vcc, 0x42800000, v169
	s_or_b64 vcc, vcc, s[6:7]
	s_cbranch_vccnz .Lattn2_slow
; #define LAS __attribute__((address_space(3)))
; __device__ __forceinline__ unsigned pk2(float lo, float hi) { f32x2_t v = {lo, hi}; bf16x2_t b = __builtin_convertvector(v, bf16x2_t); return __builtin_bit_cast(unsigned, b); }
; __device__ __forceinline__ s16x4 trrd(LAS const unsigned char* p) { return __builtin_bit_cast(s16x4, __builtin_amdgcn_ds_read_tr16_b64_v4i16((LAS v4i16_t*)p)); }
; __device__ __forceinline__ float attn_tile_exp(f32x16& st, int j, float tlf, float bsl, float rlo, float rhi) {
;     float sum = 0.f;
; #pragma unroll
;     for (int i = 0; i < 16; ++i) { const float tmp = (float)(32 * j - 64 + (i & 3) + 8 * (i >> 2)) + tlf;
;         float arg = __builtin_fmaf(-bsl, __builtin_fabsf(tmp), st[i]);
;         arg = (tmp >= rlo && tmp <= rhi) ? arg : -1.0e30f;
;         const float pe = __builtin_amdgcn_exp2f(arg); st[i] = pe; sum += pe; }
;     return sum;
; template <bool FUSED> __device__ __forceinline__ void attn_phase(const Args& a, LAS unsigned char* lds, int tid, int lane, int wave) {
;     ...
;         for (int j = 0; j < 5; ++j) {
;             f32x16 st;
; #pragma unroll
;             for (int i = 0; i < 16; ++i) st[i] = -mb;
;             LAS const unsigned char* kp = lds + (32 * wave + 32 * j + l31) * KP + 16 * h;
; #pragma unroll
;             for (int ks = 0; ks < 4; ++ks) { const bf16x8 kf = *(LAS const bf16x8*)(kp + 32 * ks); st = __builtin_amdgcn_mfma_f32_32x32x16_bf16(kf, qf[ks], st, 0, 0, 0); }
;             sum += attn_tile_exp(st, j, tlf, bsl, rlo, rhi);
; #pragma unroll
;             for (int s2 = 0; s2 < 2; ++s2) { u32x4 pw; pw.x = pk2(st[8 * s2 + 0], st[8 * s2 + 1]); pw.y = pk2(st[8 * s2 + 2], st[8 * s2 + 3]); pw.z = pk2(st[8 * s2 + 4], st[8 * s2 + 5]); pw.w = pk2(st[8 * s2 + 6], st[8 * s2 + 7]);
;                 const bf16x8 pf = __builtin_bit_cast(bf16x8, pw);
;                 LAS const unsigned char* vp = lds + LDS_VOFF + (32 * wave + 32 * j + 16 * s2 + 4 * h + q) * VP + 32 * blk + 8 * p;
; #pragma unroll
;                 for (int dt = 0; dt < 2; ++dt) { const s16x4 lo = trrd(vp + dt * 64), hi = trrd(vp + 8 * VP + dt * 64);
;                     const bf16x8 vf = __builtin_shufflevector(lo, hi, 0, 1, 2, 3, 4, 5, 6, 7);
;                     o[dt] = __builtin_amdgcn_mfma_f32_32x32x16_bf16(vf, pf, o[dt], 0, 0, 0); } }
;             __builtin_amdgcn_sched_barrier(0);
;         }
	ds_read_b128 v[172:175], v208
	ds_read_b128 v[230:233], v208 offset:32
	v_add_f32_e32 v239, 0xc2000000, v171
	v_add_f32_e32 v240, 0xc1f80000, v171
	s_waitcnt lgkmcnt(1)
	v_mfma_f32_32x32x16_bf16 v[48:63], v[172:175], v[136:139], v[32:47]
	ds_read_b128 v[172:175], v208 offset:64
	ds_read_b128 v[234:237], v208 offset:96
	v_add_f32_e32 v241, 0xc1f00000, v171
	v_add_f32_e32 v242, 0xc1e80000, v171
	s_waitcnt lgkmcnt(2)
	v_mfma_f32_32x32x16_bf16 v[48:63], v[230:233], v[132:135], v[48:63]
	v_add_f32_e32 v230, 0xc1c00000, v171
	v_add_f32_e32 v231, 0xc1b80000, v171
	s_waitcnt lgkmcnt(1)
	v_mfma_f32_32x32x16_bf16 v[48:63], v[172:175], v[128:131], v[48:63]
	s_waitcnt lgkmcnt(0)
	v_mfma_f32_32x32x16_bf16 v[48:63], v[234:237], v[140:143], v[48:63]
	s_nop 11
	v_fma_f32 v48, v170, |v239|, v48
	v_fma_f32 v49, v170, |v240|, v49
	v_fma_f32 v50, v170, |v241|, v50
	v_fma_f32 v51, v170, |v242|, v51
	v_fma_f32 v52, v170, |v230|, v52
	v_fma_f32 v53, v170, |v231|, v53
	v_exp_f32_e32 v173, v49
	v_mov_b32_e32 v49, v53
	v_exp_f32_e32 v231, v49
	v_add_f32_e32 v49, 0xc1b00000, v171
	v_exp_f32_e32 v174, v50
	v_fma_f32 v49, v170, |v49|, v54
	v_exp_f32_e32 v172, v48
	v_exp_f32_e32 v232, v49
	v_add_f32_e32 v49, 0xc1a80000, v171
	v_fma_f32 v49, v170, |v49|, v55
	v_exp_f32_e32 v175, v51
	v_exp_f32_e32 v230, v52
	v_add_f32_e32 v48, 0, v172
	v_exp_f32_e32 v55, v49
	v_add_f32_e32 v49, 0xc1800000, v171
	v_add_f32_e32 v48, v173, v48
	v_add_f32_e32 v48, v174, v48
	v_fma_f32 v49, v170, |v49|, v56
	v_add_f32_e32 v48, v175, v48
	v_add_f32_e32 v48, v230, v48
	v_exp_f32_e32 v233, v49
	v_add_f32_e32 v48, v231, v48
	v_add_f32_e32 v48, v232, v48
	v_add_f32_e32 v48, v55, v48
	v_add_f32_e32 v234, v233, v48
	v_add_f32_e32 v48, 0xc1700000, v171
	v_fma_f32 v48, v170, |v48|, v57
	v_exp_f32_e32 v235, v48
	v_add_f32_e32 v48, 0xc1600000, v171
	v_fma_f32 v48, v170, |v48|, v58
	v_exp_f32_e32 v236, v48
	v_add_f32_e32 v48, 0xc1500000, v171
	v_fma_f32 v48, v170, |v48|, v59
	v_exp_f32_e32 v237, v48
	v_add_f32_e32 v48, 0xc1000000, v171
	v_fma_f32 v48, v170, |v48|, v60
	v_exp_f32_e32 v60, v48
	v_add_f32_e32 v48, 0xc0e00000, v171
	v_fma_f32 v48, v170, |v48|, v61
	v_exp_f32_e32 v61, v48
	v_add_f32_e32 v48, 0xc0c00000, v171
	v_fma_f32 v52, v170, |v48|, v62
	ds_read_b64_tr_b16 v[48:49], v209 offset:55296
	ds_read_b64_tr_b16 v[50:51], v209 offset:56832
	ds_read_b64_tr_b16 v[58:59], v209 offset:56896
	ds_read_b64_tr_b16 v[56:57], v209 offset:55360
	v_exp_f32_e32 v62, v52
	v_add_f32_e32 v239, 0xc0a00000, v171
	v_cvt_pk_bf16_f32 v52, v172, v173
	v_cvt_pk_bf16_f32 v53, v174, v175
	v_cvt_pk_bf16_f32 v54, v230, v231
	v_cvt_pk_bf16_f32 v55, v232, v55
	s_waitcnt lgkmcnt(2)
	s_nop 0
	v_mfma_f32_32x32x16_bf16 v[16:31], v[48:51], v[52:55], v[16:31]
	v_fma_f32 v63, v170, |v239|, v63
	ds_read_b64_tr_b16 v[48:49], v209 offset:58368
	ds_read_b64_tr_b16 v[50:51], v209 offset:59904
	v_exp_f32_e32 v63, v63
	s_waitcnt lgkmcnt(2)
	v_mfma_f32_32x32x16_bf16 v[0:15], v[56:59], v[52:55], v[0:15]
	ds_read_b64_tr_b16 v[58:59], v209 offset:59968
	ds_read_b64_tr_b16 v[56:57], v209 offset:58432
	v_cvt_pk_bf16_f32 v52, v233, v235
	v_cvt_pk_bf16_f32 v53, v236, v237
	v_cvt_pk_bf16_f32 v54, v60, v61
	v_cvt_pk_bf16_f32 v55, v62, v63
	s_waitcnt lgkmcnt(2)
	s_nop 0
	v_mfma_f32_32x32x16_bf16 v[16:31], v[48:51], v[52:55], v[16:31]
	v_add_f32_e32 v48, v235, v234
	v_add_f32_e32 v48, v236, v48
	v_add_f32_e32 v48, v237, v48
	v_add_f32_e32 v48, v60, v48
	v_add_f32_e32 v48, v61, v48
	v_add_f32_e32 v48, v62, v48
	v_add_f32_e32 v48, v63, v48
	s_waitcnt lgkmcnt(0)
	v_mfma_f32_32x32x16_bf16 v[0:15], v[56:59], v[52:55], v[0:15]
	v_add_f32_e32 v238, v238, v48
	ds_read_b128 v[172:175], v210
	ds_read_b128 v[230:233], v210 offset:32
	v_add_f32_e32 v239, 1.0, v171
	s_waitcnt lgkmcnt(1)
	v_mfma_f32_32x32x16_bf16 v[48:63], v[172:175], v[136:139], v[32:47]
	ds_read_b128 v[172:175], v210 offset:64
	ds_read_b128 v[234:237], v210 offset:96
	s_waitcnt lgkmcnt(2)
	v_mfma_f32_32x32x16_bf16 v[48:63], v[230:233], v[132:135], v[48:63]
	v_add_f32_e32 v230, 2.0, v171
	v_add_f32_e32 v231, 0x40400000, v171
	v_add_f32_e32 v232, 0x41000000, v171
	s_waitcnt lgkmcnt(1)
	v_mfma_f32_32x32x16_bf16 v[48:63], v[172:175], v[128:131], v[48:63]
	v_add_f32_e32 v233, 0x41100000, v171
	s_waitcnt lgkmcnt(0)
	v_mfma_f32_32x32x16_bf16 v[48:63], v[234:237], v[140:143], v[48:63]
	s_nop 11
	v_fma_f32 v48, v170, |v171|, v48
	v_fma_f32 v49, v170, |v239|, v49
	v_fma_f32 v50, v170, |v230|, v50
	v_fma_f32 v51, v170, |v231|, v51
	v_fma_f32 v52, v170, |v232|, v52
	v_fma_f32 v53, v170, |v233|, v53
	v_exp_f32_e32 v173, v49
	v_mov_b32_e32 v49, v53
	v_exp_f32_e32 v231, v49
	v_add_f32_e32 v49, 0x41200000, v171
	v_exp_f32_e32 v174, v50
	v_fma_f32 v49, v170, |v49|, v54
	v_exp_f32_e32 v172, v48
	v_exp_f32_e32 v232, v49
	v_add_f32_e32 v49, 0x41300000, v171
	v_fma_f32 v49, v170, |v49|, v55
	v_exp_f32_e32 v175, v51
	v_exp_f32_e32 v230, v52
	v_add_f32_e32 v48, 0, v172
	v_exp_f32_e32 v55, v49
	v_add_f32_e32 v49, 0x41800000, v171
	v_add_f32_e32 v48, v173, v48
	v_add_f32_e32 v48, v174, v48
	v_fma_f32 v49, v170, |v49|, v56
	v_add_f32_e32 v48, v175, v48
	v_add_f32_e32 v48, v230, v48
	v_exp_f32_e32 v233, v49
	v_add_f32_e32 v48, v231, v48
	v_add_f32_e32 v48, v232, v48
	v_add_f32_e32 v48, v55, v48
	v_add_f32_e32 v234, v233, v48
	v_add_f32_e32 v48, 0x41880000, v171
	v_fma_f32 v48, v170, |v48|, v57
	v_exp_f32_e32 v235, v48
	v_add_f32_e32 v48, 0x41900000, v171
	v_fma_f32 v48, v170, |v48|, v58
	v_exp_f32_e32 v236, v48
	v_add_f32_e32 v48, 0x41980000, v171
	v_fma_f32 v48, v170, |v48|, v59
	v_exp_f32_e32 v237, v48
	v_add_f32_e32 v48, 0x41c00000, v171
	v_fma_f32 v48, v170, |v48|, v60
	v_exp_f32_e32 v60, v48
	v_add_f32_e32 v48, 0x41c80000, v171
	v_fma_f32 v48, v170, |v48|, v61
	v_exp_f32_e32 v61, v48
	v_add_f32_e32 v48, 0x41d00000, v171
	v_fma_f32 v52, v170, |v48|, v62
	ds_read_b64_tr_b16 v[48:49], v211 offset:55296
	ds_read_b64_tr_b16 v[50:51], v211 offset:56832
	ds_read_b64_tr_b16 v[58:59], v211 offset:56896
	ds_read_b64_tr_b16 v[56:57], v211 offset:55360
	v_exp_f32_e32 v62, v52
	v_add_f32_e32 v239, 0x41d80000, v171
	v_cvt_pk_bf16_f32 v52, v172, v173
	v_cvt_pk_bf16_f32 v53, v174, v175
	v_cvt_pk_bf16_f32 v54, v230, v231
	v_cvt_pk_bf16_f32 v55, v232, v55
	s_waitcnt lgkmcnt(2)
; #define LAS __attribute__((address_space(3)))
; __device__ __forceinline__ unsigned pk2(float lo, float hi) { f32x2_t v = {lo, hi}; bf16x2_t b = __builtin_convertvector(v, bf16x2_t); return __builtin_bit_cast(unsigned, b); }
; __device__ __forceinline__ s16x4 trrd(LAS const unsigned char* p) { return __builtin_bit_cast(s16x4, __builtin_amdgcn_ds_read_tr16_b64_v4i16((LAS v4i16_t*)p)); }
; __device__ __forceinline__ float attn_tile_exp(f32x16& st, int j, float tlf, float bsl, float rlo, float rhi) {
;     float sum = 0.f;
; #pragma unroll
;     for (int i = 0; i < 16; ++i) { const float tmp = (float)(32 * j - 64 + (i & 3) + 8 * (i >> 2)) + tlf;
;         float arg = __builtin_fmaf(-bsl, __builtin_fabsf(tmp), st[i]);
;         arg = (tmp >= rlo && tmp <= rhi) ? arg : -1.0e30f;
;         const float pe = __builtin_amdgcn_exp2f(arg); st[i] = pe; sum += pe; }
;     return sum;
; template <bool FUSED> __device__ __forceinline__ void attn_phase(const Args& a, LAS unsigned char* lds, int tid, int lane, int wave) {
;     ...
;         for (int j = 0; j < 5; ++j) {
;             f32x16 st;
; #pragma unroll
;             for (int i = 0; i < 16; ++i) st[i] = -mb;
;             LAS const unsigned char* kp = lds + (32 * wave + 32 * j + l31) * KP + 16 * h;
; #pragma unroll
;             for (int ks = 0; ks < 4; ++ks) { const bf16x8 kf = *(LAS const bf16x8*)(kp + 32 * ks); st = __builtin_amdgcn_mfma_f32_32x32x16_bf16(kf, qf[ks], st, 0, 0, 0); }
;             sum += attn_tile_exp(st, j, tlf, bsl, rlo, rhi);
; #pragma unroll
;             for (int s2 = 0; s2 < 2; ++s2) { u32x4 pw; pw.x = pk2(st[8 * s2 + 0], st[8 * s2 + 1]); pw.y = pk2(st[8 * s2 + 2], st[8 * s2 + 3]); pw.z = pk2(st[8 * s2 + 4], st[8 * s2 + 5]); pw.w = pk2(st[8 * s2 + 6], st[8 * s2 + 7]);
;                 const bf16x8 pf = __builtin_bit_cast(bf16x8, pw);
;                 LAS const unsigned char* vp = lds + LDS_VOFF + (32 * wave + 32 * j + 16 * s2 + 4 * h + q) * VP + 32 * blk + 8 * p;
; #pragma unroll
;                 for (int dt = 0; dt < 2; ++dt) { const s16x4 lo = trrd(vp + dt * 64), hi = trrd(vp + 8 * VP + dt * 64);
;                     const bf16x8 vf = __builtin_shufflevector(lo, hi, 0, 1, 2, 3, 4, 5, 6, 7);
;                     o[dt] = __builtin_amdgcn_mfma_f32_32x32x16_bf16(vf, pf, o[dt], 0, 0, 0); } }
;             __builtin_amdgcn_sched_barrier(0);
;         }
	s_nop 0
	v_mfma_f32_32x32x16_bf16 v[16:31], v[48:51], v[52:55], v[16:31]
	v_fma_f32 v63, v170, |v239|, v63
	ds_read_b64_tr_b16 v[48:49], v211 offset:58368
	ds_read_b64_tr_b16 v[50:51], v211 offset:59904
	v_exp_f32_e32 v63, v63
	s_waitcnt lgkmcnt(2)
	v_mfma_f32_32x32x16_bf16 v[0:15], v[56:59], v[52:55], v[0:15]
	ds_read_b64_tr_b16 v[58:59], v211 offset:59968
	ds_read_b64_tr_b16 v[56:57], v211 offset:58432
	v_cvt_pk_bf16_f32 v52, v233, v235
	v_cvt_pk_bf16_f32 v53, v236, v237
	v_cvt_pk_bf16_f32 v54, v60, v61
	v_cvt_pk_bf16_f32 v55, v62, v63
	s_waitcnt lgkmcnt(2)
	s_nop 0
	v_mfma_f32_32x32x16_bf16 v[16:31], v[48:51], v[52:55], v[16:31]
	v_add_f32_e32 v48, v235, v234
	v_add_f32_e32 v48, v236, v48
	v_add_f32_e32 v48, v237, v48
	v_add_f32_e32 v48, v60, v48
	v_add_f32_e32 v48, v61, v48
	v_add_f32_e32 v48, v62, v48
	v_add_f32_e32 v48, v63, v48
	s_waitcnt lgkmcnt(0)
	v_mfma_f32_32x32x16_bf16 v[0:15], v[56:59], v[52:55], v[0:15]
	v_add_f32_e32 v238, v238, v48
	ds_read_b128 v[172:175], v212
	ds_read_b128 v[230:233], v212 offset:32
	v_add_f32_e32 v239, 0x42000000, v171
	v_add_f32_e32 v240, 0x42040000, v171
	s_waitcnt lgkmcnt(1)
	v_mfma_f32_32x32x16_bf16 v[48:63], v[172:175], v[136:139], v[32:47]
	ds_read_b128 v[172:175], v212 offset:64
	ds_read_b128 v[234:237], v212 offset:96
	v_add_f32_e32 v241, 0x42080000, v171
	v_add_f32_e32 v242, 0x420c0000, v171
	s_waitcnt lgkmcnt(2)
	v_mfma_f32_32x32x16_bf16 v[48:63], v[230:233], v[132:135], v[48:63]
	v_add_f32_e32 v230, 0x42200000, v171
	v_add_f32_e32 v231, 0x42240000, v171
	s_waitcnt lgkmcnt(1)
	v_mfma_f32_32x32x16_bf16 v[48:63], v[172:175], v[128:131], v[48:63]
	s_waitcnt lgkmcnt(0)
	v_mfma_f32_32x32x16_bf16 v[48:63], v[234:237], v[140:143], v[48:63]
	s_nop 11
	v_fma_f32 v48, v170, |v239|, v48
	v_fma_f32 v49, v170, |v240|, v49
	v_fma_f32 v50, v170, |v241|, v50
	v_fma_f32 v51, v170, |v242|, v51
	v_fma_f32 v52, v170, |v230|, v52
	v_fma_f32 v53, v170, |v231|, v53
	v_exp_f32_e32 v173, v49
	v_mov_b32_e32 v49, v53
	v_exp_f32_e32 v231, v49
	v_add_f32_e32 v49, 0x42280000, v171
	v_exp_f32_e32 v174, v50
	v_fma_f32 v49, v170, |v49|, v54
	v_exp_f32_e32 v172, v48
	v_exp_f32_e32 v232, v49
	v_add_f32_e32 v49, 0x422c0000, v171
	v_fma_f32 v49, v170, |v49|, v55
	v_exp_f32_e32 v175, v51
	v_exp_f32_e32 v230, v52
	v_add_f32_e32 v48, 0, v172
	v_exp_f32_e32 v55, v49
	v_add_f32_e32 v49, 0x42400000, v171
	v_add_f32_e32 v48, v173, v48
	v_add_f32_e32 v48, v174, v48
	v_fma_f32 v49, v170, |v49|, v56
	v_add_f32_e32 v48, v175, v48
	v_add_f32_e32 v48, v230, v48
	v_exp_f32_e32 v233, v49
	v_add_f32_e32 v48, v231, v48
	v_add_f32_e32 v48, v232, v48
	v_add_f32_e32 v48, v55, v48
	v_add_f32_e32 v234, v233, v48
	v_add_f32_e32 v48, 0x42440000, v171
	v_fma_f32 v48, v170, |v48|, v57
	v_exp_f32_e32 v235, v48
	v_add_f32_e32 v48, 0x42480000, v171
	v_fma_f32 v48, v170, |v48|, v58
	v_exp_f32_e32 v236, v48
	v_add_f32_e32 v48, 0x424c0000, v171
	v_fma_f32 v48, v170, |v48|, v59
	v_exp_f32_e32 v237, v48
	v_add_f32_e32 v48, 0x42600000, v171
	v_fma_f32 v48, v170, |v48|, v60
	v_exp_f32_e32 v60, v48
	v_add_f32_e32 v48, 0x42640000, v171
	v_fma_f32 v48, v170, |v48|, v61
	v_exp_f32_e32 v61, v48
	v_add_f32_e32 v48, 0x42680000, v171
	v_fma_f32 v52, v170, |v48|, v62
	ds_read_b64_tr_b16 v[48:49], v213 offset:55296
	ds_read_b64_tr_b16 v[50:51], v213 offset:56832
	ds_read_b64_tr_b16 v[58:59], v213 offset:56896
	ds_read_b64_tr_b16 v[56:57], v213 offset:55360
	v_exp_f32_e32 v62, v52
	v_add_f32_e32 v239, 0x426c0000, v171
	v_cvt_pk_bf16_f32 v52, v172, v173
	v_cvt_pk_bf16_f32 v53, v174, v175
	v_cvt_pk_bf16_f32 v54, v230, v231
	v_cvt_pk_bf16_f32 v55, v232, v55
	s_waitcnt lgkmcnt(2)
	s_nop 0
	v_mfma_f32_32x32x16_bf16 v[16:31], v[48:51], v[52:55], v[16:31]
	v_fma_f32 v63, v170, |v239|, v63
	ds_read_b64_tr_b16 v[48:49], v213 offset:58368
	ds_read_b64_tr_b16 v[50:51], v213 offset:59904
	v_exp_f32_e32 v63, v63
	s_waitcnt lgkmcnt(2)
	v_mfma_f32_32x32x16_bf16 v[0:15], v[56:59], v[52:55], v[0:15]
	ds_read_b64_tr_b16 v[58:59], v213 offset:59968
	ds_read_b64_tr_b16 v[56:57], v213 offset:58432
	v_cvt_pk_bf16_f32 v52, v233, v235
	v_cvt_pk_bf16_f32 v53, v236, v237
	v_cvt_pk_bf16_f32 v54, v60, v61
	v_cvt_pk_bf16_f32 v55, v62, v63
	s_waitcnt lgkmcnt(2)
	s_nop 0
	v_mfma_f32_32x32x16_bf16 v[16:31], v[48:51], v[52:55], v[16:31]
	v_add_f32_e32 v48, v235, v234
	v_add_f32_e32 v48, v236, v48
	v_add_f32_e32 v48, v237, v48
	v_add_f32_e32 v48, v60, v48
	v_add_f32_e32 v48, v61, v48
	v_add_f32_e32 v48, v62, v48
	v_add_f32_e32 v48, v63, v48
	s_waitcnt lgkmcnt(0)
	v_mfma_f32_32x32x16_bf16 v[0:15], v[56:59], v[52:55], v[0:15]
	v_add_f32_e32 v60, v238, v48
	s_branch .Lattn2_t4
; #define LAS __attribute__((address_space(3)))
; __device__ __forceinline__ unsigned pk2(float lo, float hi) { f32x2_t v = {lo, hi}; bf16x2_t b = __builtin_convertvector(v, bf16x2_t); return __builtin_bit_cast(unsigned, b); }
; __device__ __forceinline__ s16x4 trrd(LAS const unsigned char* p) { return __builtin_bit_cast(s16x4, __builtin_amdgcn_ds_read_tr16_b64_v4i16((LAS v4i16_t*)p)); }
; __device__ __forceinline__ float attn_tile_exp(f32x16& st, int j, float tlf, float bsl, float rlo, float rhi) {
;     float sum = 0.f;
; #pragma unroll
;     for (int i = 0; i < 16; ++i) { const float tmp = (float)(32 * j - 64 + (i & 3) + 8 * (i >> 2)) + tlf;
;         float arg = __builtin_fmaf(-bsl, __builtin_fabsf(tmp), st[i]);
;         arg = (tmp >= rlo && tmp <= rhi) ? arg : -1.0e30f;
;         const float pe = __builtin_amdgcn_exp2f(arg); st[i] = pe; sum += pe; }
;     return sum;
; template <bool FUSED> __device__ __forceinline__ void attn_phase(const Args& a, LAS unsigned char* lds, int tid, int lane, int wave) {
;     ...
;         for (int j = 0; j < 5; ++j) {
;             f32x16 st;
; #pragma unroll
;             for (int i = 0; i < 16; ++i) st[i] = -mb;
;             LAS const unsigned char* kp = lds + (32 * wave + 32 * j + l31) * KP + 16 * h;
; #pragma unroll
;             for (int ks = 0; ks < 4; ++ks) { const bf16x8 kf = *(LAS const bf16x8*)(kp + 32 * ks); st = __builtin_amdgcn_mfma_f32_32x32x16_bf16(kf, qf[ks], st, 0, 0, 0); }
;             sum += attn_tile_exp(st, j, tlf, bsl, rlo, rhi);
; #pragma unroll
;             for (int s2 = 0; s2 < 2; ++s2) { u32x4 pw; pw.x = pk2(st[8 * s2 + 0], st[8 * s2 + 1]); pw.y = pk2(st[8 * s2 + 2], st[8 * s2 + 3]); pw.z = pk2(st[8 * s2 + 4], st[8 * s2 + 5]); pw.w = pk2(st[8 * s2 + 6], st[8 * s2 + 7]);
;                 const bf16x8 pf = __builtin_bit_cast(bf16x8, pw);
;                 LAS const unsigned char* vp = lds + LDS_VOFF + (32 * wave + 32 * j + 16 * s2 + 4 * h + q) * VP + 32 * blk + 8 * p;
; #pragma unroll
;                 for (int dt = 0; dt < 2; ++dt) { const s16x4 lo = trrd(vp + dt * 64), hi = trrd(vp + 8 * VP + dt * 64);
;                     const bf16x8 vf = __builtin_shufflevector(lo, hi, 0, 1, 2, 3, 4, 5, 6, 7);
;                     o[dt] = __builtin_amdgcn_mfma_f32_32x32x16_bf16(vf, pf, o[dt], 0, 0, 0); } }
;             __builtin_amdgcn_sched_barrier(0);
;         }
.Lattn2_slow:
	ds_read_b128 v[172:175], v208
	ds_read_b128 v[230:233], v208 offset:32
	v_add_f32_e32 v239, 0xc2000000, v171
	v_add_f32_e32 v240, 0xc1f80000, v171
	v_cmp_nge_f32_e32 vcc, v239, v168
	s_waitcnt lgkmcnt(1)
	v_mfma_f32_32x32x16_bf16 v[48:63], v[172:175], v[136:139], v[32:47]
	ds_read_b128 v[172:175], v208 offset:64
	ds_read_b128 v[234:237], v208 offset:96
	v_cmp_nle_f32_e64 s[6:7], v239, v169
	v_add_f32_e32 v241, 0xc1f00000, v171
	v_cmp_nge_f32_e64 s[8:9], v240, v168
	v_cmp_nle_f32_e64 s[10:11], v240, v169
	s_or_b64 vcc, vcc, s[6:7]
	v_add_f32_e32 v242, 0xc1e80000, v171
	s_waitcnt lgkmcnt(2)
	v_mfma_f32_32x32x16_bf16 v[48:63], v[230:233], v[132:135], v[48:63]
	v_cmp_nge_f32_e64 s[12:13], v241, v168
	v_cmp_nle_f32_e64 s[14:15], v241, v169
	v_add_f32_e32 v230, 0xc1c00000, v171
	v_cmp_nge_f32_e64 s[16:17], v242, v168
	v_cmp_nle_f32_e64 s[20:21], v242, v169
	v_add_f32_e32 v231, 0xc1b80000, v171
	v_cmp_nge_f32_e64 s[22:23], v230, v168
	s_waitcnt lgkmcnt(1)
	v_mfma_f32_32x32x16_bf16 v[48:63], v[172:175], v[128:131], v[48:63]
	v_cmp_nle_f32_e64 s[24:25], v230, v169
	v_cmp_nge_f32_e64 s[26:27], v231, v168
	v_cmp_nle_f32_e64 s[28:29], v231, v169
	s_waitcnt lgkmcnt(0)
	v_mfma_f32_32x32x16_bf16 v[48:63], v[234:237], v[140:143], v[48:63]
	s_nop 11
	v_fma_f32 v48, v170, |v239|, v48
	v_fma_f32 v49, v170, |v240|, v49
	v_cndmask_b32_e32 v48, v48, v228, vcc
	s_or_b64 vcc, s[8:9], s[10:11]
	v_fma_f32 v50, v170, |v241|, v50
	v_cndmask_b32_e32 v49, v49, v228, vcc
	s_or_b64 vcc, s[12:13], s[14:15]
	v_fma_f32 v51, v170, |v242|, v51
	v_cndmask_b32_e32 v50, v50, v228, vcc
	s_or_b64 vcc, s[16:17], s[20:21]
	v_fma_f32 v52, v170, |v230|, v52
	v_cndmask_b32_e32 v51, v51, v228, vcc
	s_or_b64 vcc, s[22:23], s[24:25]
	v_fma_f32 v53, v170, |v231|, v53
	v_cndmask_b32_e32 v52, v52, v228, vcc
	s_or_b64 vcc, s[26:27], s[28:29]
	v_exp_f32_e32 v173, v49
	v_cndmask_b32_e32 v49, v53, v228, vcc
	v_exp_f32_e32 v231, v49
	v_add_f32_e32 v49, 0xc1b00000, v171
	v_cmp_nge_f32_e32 vcc, v49, v168
	v_cmp_nle_f32_e64 s[6:7], v49, v169
	v_exp_f32_e32 v174, v50
	v_fma_f32 v50, v170, |v49|, v54
	s_or_b64 vcc, vcc, s[6:7]
	v_cndmask_b32_e32 v49, v50, v228, vcc
	v_exp_f32_e32 v172, v48
	v_exp_f32_e32 v232, v49
	v_add_f32_e32 v49, 0xc1a80000, v171
	v_cmp_nge_f32_e32 vcc, v49, v168
	v_cmp_nle_f32_e64 s[6:7], v49, v169
	v_fma_f32 v50, v170, |v49|, v55
	s_or_b64 vcc, vcc, s[6:7]
	v_exp_f32_e32 v175, v51
	v_cndmask_b32_e32 v49, v50, v228, vcc
	v_exp_f32_e32 v230, v52
	v_add_f32_e32 v48, 0, v172
	v_exp_f32_e32 v55, v49
	v_add_f32_e32 v49, 0xc1800000, v171
	v_add_f32_e32 v48, v173, v48
	v_cmp_nge_f32_e32 vcc, v49, v168
	v_cmp_nle_f32_e64 s[6:7], v49, v169
	v_add_f32_e32 v48, v174, v48
	v_fma_f32 v50, v170, |v49|, v56
	s_or_b64 vcc, vcc, s[6:7]
	v_add_f32_e32 v48, v175, v48
	v_cndmask_b32_e32 v49, v50, v228, vcc
	v_add_f32_e32 v48, v230, v48
	v_exp_f32_e32 v233, v49
	v_add_f32_e32 v48, v231, v48
	v_add_f32_e32 v48, v232, v48
	v_add_f32_e32 v48, v55, v48
	v_add_f32_e32 v234, v233, v48
	v_add_f32_e32 v48, 0xc1700000, v171
	v_cmp_nge_f32_e32 vcc, v48, v168
	v_cmp_nle_f32_e64 s[6:7], v48, v169
	v_fma_f32 v49, v170, |v48|, v57
	s_or_b64 vcc, vcc, s[6:7]
	v_cndmask_b32_e32 v48, v49, v228, vcc
	v_exp_f32_e32 v235, v48
	v_add_f32_e32 v48, 0xc1600000, v171
	v_cmp_nge_f32_e32 vcc, v48, v168
	v_cmp_nle_f32_e64 s[6:7], v48, v169
	v_fma_f32 v49, v170, |v48|, v58
	s_or_b64 vcc, vcc, s[6:7]
	v_cndmask_b32_e32 v48, v49, v228, vcc
	v_exp_f32_e32 v236, v48
	v_add_f32_e32 v48, 0xc1500000, v171
	v_cmp_nge_f32_e32 vcc, v48, v168
	v_cmp_nle_f32_e64 s[6:7], v48, v169
	v_fma_f32 v49, v170, |v48|, v59
	s_or_b64 vcc, vcc, s[6:7]
	v_cndmask_b32_e32 v48, v49, v228, vcc
	v_exp_f32_e32 v237, v48
	v_add_f32_e32 v48, 0xc1000000, v171
	v_cmp_nge_f32_e32 vcc, v48, v168
	v_cmp_nle_f32_e64 s[6:7], v48, v169
	v_fma_f32 v49, v170, |v48|, v60
	s_or_b64 vcc, vcc, s[6:7]
	v_cndmask_b32_e32 v48, v49, v228, vcc
	v_exp_f32_e32 v60, v48
	v_add_f32_e32 v48, 0xc0e00000, v171
	v_cmp_nge_f32_e32 vcc, v48, v168
	v_cmp_nle_f32_e64 s[6:7], v48, v169
	v_fma_f32 v49, v170, |v48|, v61
	s_or_b64 vcc, vcc, s[6:7]
	v_cndmask_b32_e32 v48, v49, v228, vcc
	v_exp_f32_e32 v61, v48
	v_add_f32_e32 v48, 0xc0c00000, v171
	v_cmp_nge_f32_e32 vcc, v48, v168
	v_cmp_nle_f32_e64 s[6:7], v48, v169
	v_fma_f32 v49, v170, |v48|, v62
	s_or_b64 vcc, vcc, s[6:7]
	v_cndmask_b32_e32 v52, v49, v228, vcc
	ds_read_b64_tr_b16 v[48:49], v209 offset:55296
	ds_read_b64_tr_b16 v[50:51], v209 offset:56832
	ds_read_b64_tr_b16 v[58:59], v209 offset:56896
	ds_read_b64_tr_b16 v[56:57], v209 offset:55360
	v_exp_f32_e32 v62, v52
	v_add_f32_e32 v239, 0xc0a00000, v171
	v_cvt_pk_bf16_f32 v52, v172, v173
	v_cvt_pk_bf16_f32 v53, v174, v175
	v_cvt_pk_bf16_f32 v54, v230, v231
	v_cvt_pk_bf16_f32 v55, v232, v55
	v_cmp_nge_f32_e32 vcc, v239, v168
	v_cmp_nle_f32_e64 s[6:7], v239, v169
	s_waitcnt lgkmcnt(2)
	v_mfma_f32_32x32x16_bf16 v[16:31], v[48:51], v[52:55], v[16:31]
	v_fma_f32 v48, v170, |v239|, v63
	s_or_b64 vcc, vcc, s[6:7]
	v_cndmask_b32_e32 v63, v48, v228, vcc
	ds_read_b64_tr_b16 v[48:49], v209 offset:58368
	ds_read_b64_tr_b16 v[50:51], v209 offset:59904
	v_exp_f32_e32 v63, v63
	s_waitcnt lgkmcnt(2)
	v_mfma_f32_32x32x16_bf16 v[0:15], v[56:59], v[52:55], v[0:15]
	ds_read_b64_tr_b16 v[58:59], v209 offset:59968
	ds_read_b64_tr_b16 v[56:57], v209 offset:58432
	v_cvt_pk_bf16_f32 v52, v233, v235
	v_cvt_pk_bf16_f32 v53, v236, v237
	v_cvt_pk_bf16_f32 v54, v60, v61
	v_cvt_pk_bf16_f32 v55, v62, v63
	s_waitcnt lgkmcnt(2)
	s_nop 0
	v_mfma_f32_32x32x16_bf16 v[16:31], v[48:51], v[52:55], v[16:31]
	v_add_f32_e32 v48, v235, v234
	v_add_f32_e32 v48, v236, v48
	v_add_f32_e32 v48, v237, v48
	v_add_f32_e32 v48, v60, v48
	v_add_f32_e32 v48, v61, v48
	v_add_f32_e32 v48, v62, v48
	v_add_f32_e32 v48, v63, v48
	s_waitcnt lgkmcnt(0)
; #define LAS __attribute__((address_space(3)))
; __device__ __forceinline__ unsigned pk2(float lo, float hi) { f32x2_t v = {lo, hi}; bf16x2_t b = __builtin_convertvector(v, bf16x2_t); return __builtin_bit_cast(unsigned, b); }
; __device__ __forceinline__ s16x4 trrd(LAS const unsigned char* p) { return __builtin_bit_cast(s16x4, __builtin_amdgcn_ds_read_tr16_b64_v4i16((LAS v4i16_t*)p)); }
; __device__ __forceinline__ float attn_tile_exp(f32x16& st, int j, float tlf, float bsl, float rlo, float rhi) {
;     float sum = 0.f;
; #pragma unroll
;     for (int i = 0; i < 16; ++i) { const float tmp = (float)(32 * j - 64 + (i & 3) + 8 * (i >> 2)) + tlf;
;         float arg = __builtin_fmaf(-bsl, __builtin_fabsf(tmp), st[i]);
;         arg = (tmp >= rlo && tmp <= rhi) ? arg : -1.0e30f;
;         const float pe = __builtin_amdgcn_exp2f(arg); st[i] = pe; sum += pe; }
;     return sum;
; template <bool FUSED> __device__ __forceinline__ void attn_phase(const Args& a, LAS unsigned char* lds, int tid, int lane, int wave) {
;     ...
;         for (int j = 0; j < 5; ++j) {
;             f32x16 st;
; #pragma unroll
;             for (int i = 0; i < 16; ++i) st[i] = -mb;
;             LAS const unsigned char* kp = lds + (32 * wave + 32 * j + l31) * KP + 16 * h;
; #pragma unroll
;             for (int ks = 0; ks < 4; ++ks) { const bf16x8 kf = *(LAS const bf16x8*)(kp + 32 * ks); st = __builtin_amdgcn_mfma_f32_32x32x16_bf16(kf, qf[ks], st, 0, 0, 0); }
;             sum += attn_tile_exp(st, j, tlf, bsl, rlo, rhi);
; #pragma unroll
;             for (int s2 = 0; s2 < 2; ++s2) { u32x4 pw; pw.x = pk2(st[8 * s2 + 0], st[8 * s2 + 1]); pw.y = pk2(st[8 * s2 + 2], st[8 * s2 + 3]); pw.z = pk2(st[8 * s2 + 4], st[8 * s2 + 5]); pw.w = pk2(st[8 * s2 + 6], st[8 * s2 + 7]);
;                 const bf16x8 pf = __builtin_bit_cast(bf16x8, pw);
;                 LAS const unsigned char* vp = lds + LDS_VOFF + (32 * wave + 32 * j + 16 * s2 + 4 * h + q) * VP + 32 * blk + 8 * p;
; #pragma unroll
;                 for (int dt = 0; dt < 2; ++dt) { const s16x4 lo = trrd(vp + dt * 64), hi = trrd(vp + 8 * VP + dt * 64);
;                     const bf16x8 vf = __builtin_shufflevector(lo, hi, 0, 1, 2, 3, 4, 5, 6, 7);
;                     o[dt] = __builtin_amdgcn_mfma_f32_32x32x16_bf16(vf, pf, o[dt], 0, 0, 0); } }
;             __builtin_amdgcn_sched_barrier(0);
;         }
	v_mfma_f32_32x32x16_bf16 v[0:15], v[56:59], v[52:55], v[0:15]
	v_add_f32_e32 v238, v238, v48
	ds_read_b128 v[172:175], v210
	ds_read_b128 v[230:233], v210 offset:32
	v_cmp_nge_f32_e32 vcc, v171, v168
	v_cmp_nle_f32_e64 s[6:7], v171, v169
	v_add_f32_e32 v239, 1.0, v171
	s_waitcnt lgkmcnt(1)
	v_mfma_f32_32x32x16_bf16 v[48:63], v[172:175], v[136:139], v[32:47]
	ds_read_b128 v[172:175], v210 offset:64
	ds_read_b128 v[234:237], v210 offset:96
	v_cmp_nge_f32_e64 s[8:9], v239, v168
	v_cmp_nle_f32_e64 s[10:11], v239, v169
	s_or_b64 vcc, vcc, s[6:7]
	s_waitcnt lgkmcnt(2)
	v_mfma_f32_32x32x16_bf16 v[48:63], v[230:233], v[132:135], v[48:63]
	v_add_f32_e32 v230, 2.0, v171
	v_add_f32_e32 v231, 0x40400000, v171
	v_cmp_nge_f32_e64 s[12:13], v230, v168
	v_cmp_nle_f32_e64 s[14:15], v230, v169
	v_add_f32_e32 v232, 0x41000000, v171
	v_cmp_nge_f32_e64 s[16:17], v231, v168
	v_cmp_nle_f32_e64 s[20:21], v231, v169
	s_waitcnt lgkmcnt(1)
	v_mfma_f32_32x32x16_bf16 v[48:63], v[172:175], v[128:131], v[48:63]
	v_add_f32_e32 v233, 0x41100000, v171
	v_cmp_nge_f32_e64 s[22:23], v232, v168
	v_cmp_nle_f32_e64 s[24:25], v232, v169
	v_cmp_nge_f32_e64 s[26:27], v233, v168
	v_cmp_nle_f32_e64 s[28:29], v233, v169
	s_waitcnt lgkmcnt(0)
	v_mfma_f32_32x32x16_bf16 v[48:63], v[234:237], v[140:143], v[48:63]
	s_nop 11
	v_fma_f32 v48, v170, |v171|, v48
	v_fma_f32 v49, v170, |v239|, v49
	v_cndmask_b32_e32 v48, v48, v228, vcc
	s_or_b64 vcc, s[8:9], s[10:11]
	v_fma_f32 v50, v170, |v230|, v50
	v_cndmask_b32_e32 v49, v49, v228, vcc
	s_or_b64 vcc, s[12:13], s[14:15]
	v_fma_f32 v51, v170, |v231|, v51
	v_cndmask_b32_e32 v50, v50, v228, vcc
	s_or_b64 vcc, s[16:17], s[20:21]
	v_fma_f32 v52, v170, |v232|, v52
	v_cndmask_b32_e32 v51, v51, v228, vcc
	s_or_b64 vcc, s[22:23], s[24:25]
	v_fma_f32 v53, v170, |v233|, v53
	v_cndmask_b32_e32 v52, v52, v228, vcc
	s_or_b64 vcc, s[26:27], s[28:29]
	v_exp_f32_e32 v173, v49
	v_cndmask_b32_e32 v49, v53, v228, vcc
	v_exp_f32_e32 v231, v49
	v_add_f32_e32 v49, 0x41200000, v171
	v_cmp_nge_f32_e32 vcc, v49, v168
	v_cmp_nle_f32_e64 s[6:7], v49, v169
	v_exp_f32_e32 v174, v50
	v_fma_f32 v50, v170, |v49|, v54
	s_or_b64 vcc, vcc, s[6:7]
	v_cndmask_b32_e32 v49, v50, v228, vcc
	v_exp_f32_e32 v172, v48
	v_exp_f32_e32 v232, v49
	v_add_f32_e32 v49, 0x41300000, v171
	v_cmp_nge_f32_e32 vcc, v49, v168
	v_cmp_nle_f32_e64 s[6:7], v49, v169
	v_fma_f32 v50, v170, |v49|, v55
	s_or_b64 vcc, vcc, s[6:7]
	v_exp_f32_e32 v175, v51
	v_cndmask_b32_e32 v49, v50, v228, vcc
	v_exp_f32_e32 v230, v52
	v_add_f32_e32 v48, 0, v172
	v_exp_f32_e32 v55, v49
	v_add_f32_e32 v49, 0x41800000, v171
	v_add_f32_e32 v48, v173, v48
	v_cmp_nge_f32_e32 vcc, v49, v168
	v_cmp_nle_f32_e64 s[6:7], v49, v169
	v_add_f32_e32 v48, v174, v48
	v_fma_f32 v50, v170, |v49|, v56
	s_or_b64 vcc, vcc, s[6:7]
	v_add_f32_e32 v48, v175, v48
	v_cndmask_b32_e32 v49, v50, v228, vcc
	v_add_f32_e32 v48, v230, v48
	v_exp_f32_e32 v233, v49
	v_add_f32_e32 v48, v231, v48
	v_add_f32_e32 v48, v232, v48
	v_add_f32_e32 v48, v55, v48
	v_add_f32_e32 v234, v233, v48
	v_add_f32_e32 v48, 0x41880000, v171
	v_cmp_nge_f32_e32 vcc, v48, v168
	v_cmp_nle_f32_e64 s[6:7], v48, v169
	v_fma_f32 v49, v170, |v48|, v57
	s_or_b64 vcc, vcc, s[6:7]
	v_cndmask_b32_e32 v48, v49, v228, vcc
	v_exp_f32_e32 v235, v48
	v_add_f32_e32 v48, 0x41900000, v171
	v_cmp_nge_f32_e32 vcc, v48, v168
	v_cmp_nle_f32_e64 s[6:7], v48, v169
	v_fma_f32 v49, v170, |v48|, v58
	s_or_b64 vcc, vcc, s[6:7]
	v_cndmask_b32_e32 v48, v49, v228, vcc
	v_exp_f32_e32 v236, v48
	v_add_f32_e32 v48, 0x41980000, v171
	v_cmp_nge_f32_e32 vcc, v48, v168
	v_cmp_nle_f32_e64 s[6:7], v48, v169
	v_fma_f32 v49, v170, |v48|, v59
	s_or_b64 vcc, vcc, s[6:7]
	v_cndmask_b32_e32 v48, v49, v228, vcc
	v_exp_f32_e32 v237, v48
	v_add_f32_e32 v48, 0x41c00000, v171
	v_cmp_nge_f32_e32 vcc, v48, v168
	v_cmp_nle_f32_e64 s[6:7], v48, v169
	v_fma_f32 v49, v170, |v48|, v60
	s_or_b64 vcc, vcc, s[6:7]
	v_cndmask_b32_e32 v48, v49, v228, vcc
	v_exp_f32_e32 v60, v48
	v_add_f32_e32 v48, 0x41c80000, v171
	v_cmp_nge_f32_e32 vcc, v48, v168
	v_cmp_nle_f32_e64 s[6:7], v48, v169
	v_fma_f32 v49, v170, |v48|, v61
	s_or_b64 vcc, vcc, s[6:7]
	v_cndmask_b32_e32 v48, v49, v228, vcc
	v_exp_f32_e32 v61, v48
	v_add_f32_e32 v48, 0x41d00000, v171
	v_cmp_nge_f32_e32 vcc, v48, v168
	v_cmp_nle_f32_e64 s[6:7], v48, v169
	v_fma_f32 v49, v170, |v48|, v62
	s_or_b64 vcc, vcc, s[6:7]
	v_cndmask_b32_e32 v52, v49, v228, vcc
	ds_read_b64_tr_b16 v[48:49], v211 offset:55296
	ds_read_b64_tr_b16 v[50:51], v211 offset:56832
	ds_read_b64_tr_b16 v[58:59], v211 offset:56896
	ds_read_b64_tr_b16 v[56:57], v211 offset:55360
	v_exp_f32_e32 v62, v52
	v_add_f32_e32 v239, 0x41d80000, v171
	v_cvt_pk_bf16_f32 v52, v172, v173
	v_cvt_pk_bf16_f32 v53, v174, v175
	v_cvt_pk_bf16_f32 v54, v230, v231
	v_cvt_pk_bf16_f32 v55, v232, v55
	v_cmp_nge_f32_e32 vcc, v239, v168
	v_cmp_nle_f32_e64 s[6:7], v239, v169
	s_waitcnt lgkmcnt(2)
	v_mfma_f32_32x32x16_bf16 v[16:31], v[48:51], v[52:55], v[16:31]
	v_fma_f32 v48, v170, |v239|, v63
	s_or_b64 vcc, vcc, s[6:7]
	v_cndmask_b32_e32 v63, v48, v228, vcc
	ds_read_b64_tr_b16 v[48:49], v211 offset:58368
	ds_read_b64_tr_b16 v[50:51], v211 offset:59904
	v_exp_f32_e32 v63, v63
	s_waitcnt lgkmcnt(2)
	v_mfma_f32_32x32x16_bf16 v[0:15], v[56:59], v[52:55], v[0:15]
	ds_read_b64_tr_b16 v[58:59], v211 offset:59968
	ds_read_b64_tr_b16 v[56:57], v211 offset:58432
	v_cvt_pk_bf16_f32 v52, v233, v235
	v_cvt_pk_bf16_f32 v53, v236, v237
	v_cvt_pk_bf16_f32 v54, v60, v61
	v_cvt_pk_bf16_f32 v55, v62, v63
	s_waitcnt lgkmcnt(2)
; #define LAS __attribute__((address_space(3)))
; __device__ __forceinline__ unsigned pk2(float lo, float hi) { f32x2_t v = {lo, hi}; bf16x2_t b = __builtin_convertvector(v, bf16x2_t); return __builtin_bit_cast(unsigned, b); }
; __device__ __forceinline__ s16x4 trrd(LAS const unsigned char* p) { return __builtin_bit_cast(s16x4, __builtin_amdgcn_ds_read_tr16_b64_v4i16((LAS v4i16_t*)p)); }
; __device__ __forceinline__ float attn_tile_exp(f32x16& st, int j, float tlf, float bsl, float rlo, float rhi) {
;     float sum = 0.f;
; #pragma unroll
;     for (int i = 0; i < 16; ++i) { const float tmp = (float)(32 * j - 64 + (i & 3) + 8 * (i >> 2)) + tlf;
;         float arg = __builtin_fmaf(-bsl, __builtin_fabsf(tmp), st[i]);
;         arg = (tmp >= rlo && tmp <= rhi) ? arg : -1.0e30f;
;         const float pe = __builtin_amdgcn_exp2f(arg); st[i] = pe; sum += pe; }
;     return sum;
; template <bool FUSED> __device__ __forceinline__ void attn_phase(const Args& a, LAS unsigned char* lds, int tid, int lane, int wave) {
;     ...
;         for (int j = 0; j < 5; ++j) {
;             f32x16 st;
; #pragma unroll
;             for (int i = 0; i < 16; ++i) st[i] = -mb;
;             LAS const unsigned char* kp = lds + (32 * wave + 32 * j + l31) * KP + 16 * h;
; #pragma unroll
;             for (int ks = 0; ks < 4; ++ks) { const bf16x8 kf = *(LAS const bf16x8*)(kp + 32 * ks); st = __builtin_amdgcn_mfma_f32_32x32x16_bf16(kf, qf[ks], st, 0, 0, 0); }
;             sum += attn_tile_exp(st, j, tlf, bsl, rlo, rhi);
; #pragma unroll
;             for (int s2 = 0; s2 < 2; ++s2) { u32x4 pw; pw.x = pk2(st[8 * s2 + 0], st[8 * s2 + 1]); pw.y = pk2(st[8 * s2 + 2], st[8 * s2 + 3]); pw.z = pk2(st[8 * s2 + 4], st[8 * s2 + 5]); pw.w = pk2(st[8 * s2 + 6], st[8 * s2 + 7]);
;                 const bf16x8 pf = __builtin_bit_cast(bf16x8, pw);
;                 LAS const unsigned char* vp = lds + LDS_VOFF + (32 * wave + 32 * j + 16 * s2 + 4 * h + q) * VP + 32 * blk + 8 * p;
; #pragma unroll
;                 for (int dt = 0; dt < 2; ++dt) { const s16x4 lo = trrd(vp + dt * 64), hi = trrd(vp + 8 * VP + dt * 64);
;                     const bf16x8 vf = __builtin_shufflevector(lo, hi, 0, 1, 2, 3, 4, 5, 6, 7);
;                     o[dt] = __builtin_amdgcn_mfma_f32_32x32x16_bf16(vf, pf, o[dt], 0, 0, 0); } }
;             __builtin_amdgcn_sched_barrier(0);
;         }
	s_nop 0
	v_mfma_f32_32x32x16_bf16 v[16:31], v[48:51], v[52:55], v[16:31]
	v_add_f32_e32 v48, v235, v234
	v_add_f32_e32 v48, v236, v48
	v_add_f32_e32 v48, v237, v48
	v_add_f32_e32 v48, v60, v48
	v_add_f32_e32 v48, v61, v48
	v_add_f32_e32 v48, v62, v48
	v_add_f32_e32 v48, v63, v48
	s_waitcnt lgkmcnt(0)
	v_mfma_f32_32x32x16_bf16 v[0:15], v[56:59], v[52:55], v[0:15]
	v_add_f32_e32 v238, v238, v48
	ds_read_b128 v[172:175], v212
	ds_read_b128 v[230:233], v212 offset:32
	v_add_f32_e32 v239, 0x42000000, v171
	v_add_f32_e32 v240, 0x42040000, v171
	v_cmp_nge_f32_e32 vcc, v239, v168
	s_waitcnt lgkmcnt(1)
	v_mfma_f32_32x32x16_bf16 v[48:63], v[172:175], v[136:139], v[32:47]
	ds_read_b128 v[172:175], v212 offset:64
	ds_read_b128 v[234:237], v212 offset:96
	v_cmp_nle_f32_e64 s[6:7], v239, v169
	v_add_f32_e32 v241, 0x42080000, v171
	v_cmp_nge_f32_e64 s[8:9], v240, v168
	v_cmp_nle_f32_e64 s[10:11], v240, v169
	s_or_b64 vcc, vcc, s[6:7]
	v_add_f32_e32 v242, 0x420c0000, v171
	s_waitcnt lgkmcnt(2)
	v_mfma_f32_32x32x16_bf16 v[48:63], v[230:233], v[132:135], v[48:63]
	v_cmp_nge_f32_e64 s[12:13], v241, v168
	v_cmp_nle_f32_e64 s[14:15], v241, v169
	v_add_f32_e32 v230, 0x42200000, v171
	v_cmp_nge_f32_e64 s[16:17], v242, v168
	v_cmp_nle_f32_e64 s[20:21], v242, v169
	v_add_f32_e32 v231, 0x42240000, v171
	v_cmp_nge_f32_e64 s[22:23], v230, v168
	s_waitcnt lgkmcnt(1)
	v_mfma_f32_32x32x16_bf16 v[48:63], v[172:175], v[128:131], v[48:63]
	v_cmp_nle_f32_e64 s[24:25], v230, v169
	v_cmp_nge_f32_e64 s[26:27], v231, v168
	v_cmp_nle_f32_e64 s[28:29], v231, v169
	s_waitcnt lgkmcnt(0)
	v_mfma_f32_32x32x16_bf16 v[48:63], v[234:237], v[140:143], v[48:63]
	s_nop 11
	v_fma_f32 v48, v170, |v239|, v48
	v_fma_f32 v49, v170, |v240|, v49
	v_cndmask_b32_e32 v48, v48, v228, vcc
	s_or_b64 vcc, s[8:9], s[10:11]
	v_fma_f32 v50, v170, |v241|, v50
	v_cndmask_b32_e32 v49, v49, v228, vcc
	s_or_b64 vcc, s[12:13], s[14:15]
	v_fma_f32 v51, v170, |v242|, v51
	v_cndmask_b32_e32 v50, v50, v228, vcc
	s_or_b64 vcc, s[16:17], s[20:21]
	v_fma_f32 v52, v170, |v230|, v52
	v_cndmask_b32_e32 v51, v51, v228, vcc
	s_or_b64 vcc, s[22:23], s[24:25]
	v_fma_f32 v53, v170, |v231|, v53
	v_cndmask_b32_e32 v52, v52, v228, vcc
	s_or_b64 vcc, s[26:27], s[28:29]
	v_exp_f32_e32 v173, v49
	v_cndmask_b32_e32 v49, v53, v228, vcc
	v_exp_f32_e32 v231, v49
	v_add_f32_e32 v49, 0x42280000, v171
	v_cmp_nge_f32_e32 vcc, v49, v168
	v_cmp_nle_f32_e64 s[6:7], v49, v169
	v_exp_f32_e32 v174, v50
	v_fma_f32 v50, v170, |v49|, v54
	s_or_b64 vcc, vcc, s[6:7]
	v_cndmask_b32_e32 v49, v50, v228, vcc
	v_exp_f32_e32 v172, v48
	v_exp_f32_e32 v232, v49
	v_add_f32_e32 v49, 0x422c0000, v171
	v_cmp_nge_f32_e32 vcc, v49, v168
	v_cmp_nle_f32_e64 s[6:7], v49, v169
	v_fma_f32 v50, v170, |v49|, v55
	s_or_b64 vcc, vcc, s[6:7]
	v_exp_f32_e32 v175, v51
	v_cndmask_b32_e32 v49, v50, v228, vcc
	v_exp_f32_e32 v230, v52
	v_add_f32_e32 v48, 0, v172
	v_exp_f32_e32 v55, v49
	v_add_f32_e32 v49, 0x42400000, v171
	v_add_f32_e32 v48, v173, v48
	v_cmp_nge_f32_e32 vcc, v49, v168
	v_cmp_nle_f32_e64 s[6:7], v49, v169
	v_add_f32_e32 v48, v174, v48
	v_fma_f32 v50, v170, |v49|, v56
	s_or_b64 vcc, vcc, s[6:7]
	v_add_f32_e32 v48, v175, v48
	v_cndmask_b32_e32 v49, v50, v228, vcc
	v_add_f32_e32 v48, v230, v48
	v_exp_f32_e32 v233, v49
	v_add_f32_e32 v48, v231, v48
	v_add_f32_e32 v48, v232, v48
	v_add_f32_e32 v48, v55, v48
	v_add_f32_e32 v234, v233, v48
	v_add_f32_e32 v48, 0x42440000, v171
	v_cmp_nge_f32_e32 vcc, v48, v168
	v_cmp_nle_f32_e64 s[6:7], v48, v169
	v_fma_f32 v49, v170, |v48|, v57
	s_or_b64 vcc, vcc, s[6:7]
	v_cndmask_b32_e32 v48, v49, v228, vcc
	v_exp_f32_e32 v235, v48
	v_add_f32_e32 v48, 0x42480000, v171
	v_cmp_nge_f32_e32 vcc, v48, v168
	v_cmp_nle_f32_e64 s[6:7], v48, v169
	v_fma_f32 v49, v170, |v48|, v58
	s_or_b64 vcc, vcc, s[6:7]
	v_cndmask_b32_e32 v48, v49, v228, vcc
	v_exp_f32_e32 v236, v48
	v_add_f32_e32 v48, 0x424c0000, v171
	v_cmp_nge_f32_e32 vcc, v48, v168
	v_cmp_nle_f32_e64 s[6:7], v48, v169
	v_fma_f32 v49, v170, |v48|, v59
	s_or_b64 vcc, vcc, s[6:7]
	v_cndmask_b32_e32 v48, v49, v228, vcc
	v_exp_f32_e32 v237, v48
	v_add_f32_e32 v48, 0x42600000, v171
	v_cmp_nge_f32_e32 vcc, v48, v168
	v_cmp_nle_f32_e64 s[6:7], v48, v169
	v_fma_f32 v49, v170, |v48|, v60
	s_or_b64 vcc, vcc, s[6:7]
	v_cndmask_b32_e32 v48, v49, v228, vcc
	v_exp_f32_e32 v60, v48
	v_add_f32_e32 v48, 0x42640000, v171
	v_cmp_nge_f32_e32 vcc, v48, v168
	v_cmp_nle_f32_e64 s[6:7], v48, v169
	v_fma_f32 v49, v170, |v48|, v61
	s_or_b64 vcc, vcc, s[6:7]
	v_cndmask_b32_e32 v48, v49, v228, vcc
	v_exp_f32_e32 v61, v48
	v_add_f32_e32 v48, 0x42680000, v171
	v_cmp_nge_f32_e32 vcc, v48, v168
	v_cmp_nle_f32_e64 s[6:7], v48, v169
	v_fma_f32 v49, v170, |v48|, v62
	s_or_b64 vcc, vcc, s[6:7]
	v_cndmask_b32_e32 v52, v49, v228, vcc
	ds_read_b64_tr_b16 v[48:49], v213 offset:55296
	ds_read_b64_tr_b16 v[50:51], v213 offset:56832
	ds_read_b64_tr_b16 v[58:59], v213 offset:56896
	ds_read_b64_tr_b16 v[56:57], v213 offset:55360
	v_exp_f32_e32 v62, v52
	v_add_f32_e32 v239, 0x426c0000, v171
	v_cvt_pk_bf16_f32 v52, v172, v173
	v_cvt_pk_bf16_f32 v53, v174, v175
	v_cvt_pk_bf16_f32 v54, v230, v231
	v_cvt_pk_bf16_f32 v55, v232, v55
	v_cmp_nge_f32_e32 vcc, v239, v168
	v_cmp_nle_f32_e64 s[6:7], v239, v169
	s_waitcnt lgkmcnt(2)
	v_mfma_f32_32x32x16_bf16 v[16:31], v[48:51], v[52:55], v[16:31]
	v_fma_f32 v48, v170, |v239|, v63
	s_or_b64 vcc, vcc, s[6:7]
	v_cndmask_b32_e32 v63, v48, v228, vcc
	ds_read_b64_tr_b16 v[48:49], v213 offset:58368
	ds_read_b64_tr_b16 v[50:51], v213 offset:59904
	v_exp_f32_e32 v63, v63
	s_waitcnt lgkmcnt(2)
	v_mfma_f32_32x32x16_bf16 v[0:15], v[56:59], v[52:55], v[0:15]
	ds_read_b64_tr_b16 v[58:59], v213 offset:59968
	ds_read_b64_tr_b16 v[56:57], v213 offset:58432
	v_cvt_pk_bf16_f32 v52, v233, v235
	v_cvt_pk_bf16_f32 v53, v236, v237
	v_cvt_pk_bf16_f32 v54, v60, v61
	v_cvt_pk_bf16_f32 v55, v62, v63
	s_waitcnt lgkmcnt(2)
	s_nop 0
	v_mfma_f32_32x32x16_bf16 v[16:31], v[48:51], v[52:55], v[16:31]
	v_add_f32_e32 v48, v235, v234
	v_add_f32_e32 v48, v236, v48
	v_add_f32_e32 v48, v237, v48
	v_add_f32_e32 v48, v60, v48
	v_add_f32_e32 v48, v61, v48
	v_add_f32_e32 v48, v62, v48
	v_add_f32_e32 v48, v63, v48
	s_waitcnt lgkmcnt(0)
	v_mfma_f32_32x32x16_bf16 v[0:15], v[56:59], v[52:55], v[0:15]
	v_add_f32_e32 v60, v238, v48
; #define LAS __attribute__((address_space(3)))
; __device__ __forceinline__ unsigned pk2(float lo, float hi) { f32x2_t v = {lo, hi}; bf16x2_t b = __builtin_convertvector(v, bf16x2_t); return __builtin_bit_cast(unsigned, b); }
; __device__ __forceinline__ s16x4 trrd(LAS const unsigned char* p) { return __builtin_bit_cast(s16x4, __builtin_amdgcn_ds_read_tr16_b64_v4i16((LAS v4i16_t*)p)); }
; #define ATTN_QLOAD(W) do { const bf16_t* qr_ = Qb + ((size_t)((W).b * 24 + (W).hd) * SEQ + (size_t)((W).r * (W).L + (W).i0 + 32 * wave + l31)) * 64; \
;         _Pragma("unroll") for (int ks_ = 0; ks_ < 4; ++ks_) qv[ks_] = *(const u32x4*)(qr_ + 16 * ks_ + 8 * h); } while (0)
; template <bool FUSED> __device__ __forceinline__ void attn_phase(const Args& a, LAS unsigned char* lds, int tid, int lane, int wave) {
;     ...
;         for (int j = 0; j < 5; ++j) {
;             f32x16 st;
; #pragma unroll
;             for (int i = 0; i < 16; ++i) st[i] = -mb;
;             LAS const unsigned char* kp = lds + (32 * wave + 32 * j + l31) * KP + 16 * h;
; #pragma unroll
;             for (int ks = 0; ks < 4; ++ks) { const bf16x8 kf = *(LAS const bf16x8*)(kp + 32 * ks); st = __builtin_amdgcn_mfma_f32_32x32x16_bf16(kf, qf[ks], st, 0, 0, 0); }
;             sum += attn_tile_exp(st, j, tlf, bsl, rlo, rhi);
; #pragma unroll
;             for (int s2 = 0; s2 < 2; ++s2) { u32x4 pw; pw.x = pk2(st[8 * s2 + 0], st[8 * s2 + 1]); pw.y = pk2(st[8 * s2 + 2], st[8 * s2 + 3]); pw.z = pk2(st[8 * s2 + 4], st[8 * s2 + 5]); pw.w = pk2(st[8 * s2 + 6], st[8 * s2 + 7]);
;                 const bf16x8 pf = __builtin_bit_cast(bf16x8, pw);
;                 LAS const unsigned char* vp = lds + LDS_VOFF + (32 * wave + 32 * j + 16 * s2 + 4 * h + q) * VP + 32 * blk + 8 * p;
; #pragma unroll
;                 for (int dt = 0; dt < 2; ++dt) { const s16x4 lo = trrd(vp + dt * 64), hi = trrd(vp + 8 * VP + dt * 64);
;                     const bf16x8 vf = __builtin_shufflevector(lo, hi, 0, 1, 2, 3, 4, 5, 6, 7);
;                     o[dt] = __builtin_amdgcn_mfma_f32_32x32x16_bf16(vf, pf, o[dt], 0, 0, 0); } }
;             __builtin_amdgcn_sched_barrier(0);
;         }
;         sum += __shfl_xor(sum, 32);
;         if (un < NU) { const AUnit wq = attn_decode(un, HD0, NH); ATTN_QLOAD(wq); }
.Lattn2_t4:
	ds_read_b128 v[48:51], v214
	ds_read_b128 v[52:55], v214 offset:32
	v_add_f32_e32 v61, 0x42800000, v171
	v_add_f32_e32 v62, 0x42820000, v171
	v_cmp_nge_f32_e32 vcc, v61, v168
	s_waitcnt lgkmcnt(1)
	v_mfma_f32_32x32x16_bf16 v[32:47], v[48:51], v[136:139], v[32:47]
	ds_read_b128 v[48:51], v214 offset:64
	ds_read_b128 v[56:59], v214 offset:96
	v_cmp_nle_f32_e64 s[6:7], v61, v169
	v_add_f32_e32 v63, 0x42840000, v171
	v_cmp_nge_f32_e64 s[8:9], v62, v168
	v_cmp_nle_f32_e64 s[10:11], v62, v169
	s_or_b64 vcc, vcc, s[6:7]
	v_add_f32_e32 v136, 0x42860000, v171
	s_waitcnt lgkmcnt(2)
	v_mfma_f32_32x32x16_bf16 v[32:47], v[52:55], v[132:135], v[32:47]
	v_cmp_nge_f32_e64 s[12:13], v63, v168
	v_cmp_nle_f32_e64 s[14:15], v63, v169
	v_add_f32_e32 v52, 0x42900000, v171
	v_cmp_nge_f32_e64 s[16:17], v136, v168
	v_cmp_nle_f32_e64 s[20:21], v136, v169
	v_add_f32_e32 v53, 0x42920000, v171
	v_cmp_nge_f32_e64 s[22:23], v52, v168
	s_waitcnt lgkmcnt(1)
	v_mfma_f32_32x32x16_bf16 v[32:47], v[48:51], v[128:131], v[32:47]
	v_cmp_nle_f32_e64 s[24:25], v52, v169
	v_cmp_nge_f32_e64 s[26:27], v53, v168
	v_cmp_nle_f32_e64 s[28:29], v53, v169
	s_waitcnt lgkmcnt(0)
	v_mfma_f32_32x32x16_bf16 v[32:47], v[56:59], v[140:143], v[32:47]
	s_nop 11
	v_fma_f32 v32, v170, |v61|, v32
	v_fma_f32 v33, v170, |v62|, v33
	v_cndmask_b32_e32 v32, v32, v228, vcc
	s_or_b64 vcc, s[8:9], s[10:11]
	v_fma_f32 v34, v170, |v63|, v34
	v_cndmask_b32_e32 v33, v33, v228, vcc
	s_or_b64 vcc, s[12:13], s[14:15]
	v_fma_f32 v35, v170, |v136|, v35
	v_cndmask_b32_e32 v34, v34, v228, vcc
	s_or_b64 vcc, s[16:17], s[20:21]
	v_fma_f32 v36, v170, |v52|, v36
	v_cndmask_b32_e32 v35, v35, v228, vcc
	s_or_b64 vcc, s[22:23], s[24:25]
	v_fma_f32 v37, v170, |v53|, v37
	v_cndmask_b32_e32 v36, v36, v228, vcc
	s_or_b64 vcc, s[26:27], s[28:29]
	v_exp_f32_e32 v49, v33
	v_cndmask_b32_e32 v33, v37, v228, vcc
	v_exp_f32_e32 v53, v33
	v_add_f32_e32 v33, 0x42940000, v171
	v_cmp_nge_f32_e32 vcc, v33, v168
	v_cmp_nle_f32_e64 s[6:7], v33, v169
	v_exp_f32_e32 v50, v34
	v_fma_f32 v34, v170, |v33|, v38
	s_or_b64 vcc, vcc, s[6:7]
	v_cndmask_b32_e32 v33, v34, v228, vcc
	v_exp_f32_e32 v48, v32
	v_exp_f32_e32 v54, v33
	v_add_f32_e32 v33, 0x42960000, v171
	v_cmp_nge_f32_e32 vcc, v33, v168
	v_cmp_nle_f32_e64 s[6:7], v33, v169
	v_fma_f32 v34, v170, |v33|, v39
	s_or_b64 vcc, vcc, s[6:7]
	v_exp_f32_e32 v51, v35
	v_cndmask_b32_e32 v33, v34, v228, vcc
	v_exp_f32_e32 v52, v36
	v_add_f32_e32 v32, 0, v48
	v_exp_f32_e32 v39, v33
	v_add_f32_e32 v33, 0x42a00000, v171
	v_add_f32_e32 v32, v49, v32
	v_cmp_nge_f32_e32 vcc, v33, v168
	v_cmp_nle_f32_e64 s[6:7], v33, v169
	v_add_f32_e32 v32, v50, v32
	v_fma_f32 v34, v170, |v33|, v40
	s_or_b64 vcc, vcc, s[6:7]
	v_add_f32_e32 v32, v51, v32
	v_cndmask_b32_e32 v33, v34, v228, vcc
	v_add_f32_e32 v32, v52, v32
	v_exp_f32_e32 v55, v33
	v_add_f32_e32 v32, v53, v32
	v_add_f32_e32 v32, v54, v32
	v_add_f32_e32 v32, v39, v32
	v_add_f32_e32 v56, v55, v32
	v_add_f32_e32 v32, 0x42a20000, v171
	v_cmp_nge_f32_e32 vcc, v32, v168
	v_cmp_nle_f32_e64 s[6:7], v32, v169
	v_fma_f32 v33, v170, |v32|, v41
	s_or_b64 vcc, vcc, s[6:7]
	v_cndmask_b32_e32 v32, v33, v228, vcc
	v_exp_f32_e32 v57, v32
	v_add_f32_e32 v32, 0x42a40000, v171
	v_cmp_nge_f32_e32 vcc, v32, v168
	v_cmp_nle_f32_e64 s[6:7], v32, v169
	v_fma_f32 v33, v170, |v32|, v42
	s_or_b64 vcc, vcc, s[6:7]
	v_cndmask_b32_e32 v32, v33, v228, vcc
	v_exp_f32_e32 v58, v32
	v_add_f32_e32 v32, 0x42a60000, v171
	v_cmp_nge_f32_e32 vcc, v32, v168
	v_cmp_nle_f32_e64 s[6:7], v32, v169
	v_fma_f32 v33, v170, |v32|, v43
	s_or_b64 vcc, vcc, s[6:7]
	v_cndmask_b32_e32 v32, v33, v228, vcc
	v_exp_f32_e32 v59, v32
	v_add_f32_e32 v32, 0x42b00000, v171
	v_cmp_nge_f32_e32 vcc, v32, v168
	v_cmp_nle_f32_e64 s[6:7], v32, v169
	v_fma_f32 v33, v170, |v32|, v44
	s_or_b64 vcc, vcc, s[6:7]
	v_cndmask_b32_e32 v32, v33, v228, vcc
	v_exp_f32_e32 v44, v32
	v_add_f32_e32 v32, 0x42b20000, v171
	v_cmp_nge_f32_e32 vcc, v32, v168
	v_cmp_nle_f32_e64 s[6:7], v32, v169
	v_fma_f32 v33, v170, |v32|, v45
	s_or_b64 vcc, vcc, s[6:7]
	v_cndmask_b32_e32 v32, v33, v228, vcc
	v_exp_f32_e32 v45, v32
	v_add_f32_e32 v32, 0x42b40000, v171
	v_cmp_nge_f32_e32 vcc, v32, v168
	v_cmp_nle_f32_e64 s[6:7], v32, v169
	v_fma_f32 v33, v170, |v32|, v46
	s_or_b64 vcc, vcc, s[6:7]
	v_cndmask_b32_e32 v36, v33, v228, vcc
	ds_read_b64_tr_b16 v[32:33], v215 offset:55296
	ds_read_b64_tr_b16 v[34:35], v215 offset:56832
	ds_read_b64_tr_b16 v[42:43], v215 offset:56896
	ds_read_b64_tr_b16 v[40:41], v215 offset:55360
	v_exp_f32_e32 v46, v36
	v_add_f32_e32 v61, 0x42b60000, v171
	v_cvt_pk_bf16_f32 v36, v48, v49
	v_cvt_pk_bf16_f32 v37, v50, v51
	v_cvt_pk_bf16_f32 v38, v52, v53
	v_cvt_pk_bf16_f32 v39, v54, v39
	v_cmp_nge_f32_e32 vcc, v61, v168
	v_cmp_nle_f32_e64 s[6:7], v61, v169
	s_waitcnt lgkmcnt(2)
	v_mfma_f32_32x32x16_bf16 v[16:31], v[32:35], v[36:39], v[16:31]
	v_fma_f32 v32, v170, |v61|, v47
	s_or_b64 vcc, vcc, s[6:7]
	v_cndmask_b32_e32 v47, v32, v228, vcc
	ds_read_b64_tr_b16 v[32:33], v215 offset:58368
	ds_read_b64_tr_b16 v[34:35], v215 offset:59904
	v_exp_f32_e32 v47, v47
	s_waitcnt lgkmcnt(2)
	v_mfma_f32_32x32x16_bf16 v[0:15], v[40:43], v[36:39], v[0:15]
	ds_read_b64_tr_b16 v[42:43], v215 offset:59968
	ds_read_b64_tr_b16 v[40:41], v215 offset:58432
	v_cvt_pk_bf16_f32 v36, v55, v57
	v_cvt_pk_bf16_f32 v37, v58, v59
	v_cvt_pk_bf16_f32 v38, v44, v45
	v_cvt_pk_bf16_f32 v39, v46, v47
	s_waitcnt lgkmcnt(2)
	s_nop 0
	v_mfma_f32_32x32x16_bf16 v[16:31], v[32:35], v[36:39], v[16:31]
	v_add_f32_e32 v32, v57, v56
	v_add_f32_e32 v32, v58, v32
	v_add_f32_e32 v32, v59, v32
	v_add_f32_e32 v32, v44, v32
	v_add_f32_e32 v32, v45, v32
	v_add_f32_e32 v32, v46, v32
	v_add_f32_e32 v32, v47, v32
	s_waitcnt lgkmcnt(0)
	v_mfma_f32_32x32x16_bf16 v[0:15], v[40:43], v[36:39], v[0:15]
	v_add_f32_e32 v236, v60, v32
	ds_bpermute_b32 v237, v151, v236
	s_andn2_b64 vcc, exec, s[44:45]
	s_cbranch_vccnz .LBB0_406
	s_ashr_i32 s7, s64, 5
	s_lshr_b32 s8, s7, 29
	s_add_i32 s8, s7, s8
	s_and_b32 s8, s8, -8
	s_sub_i32 s7, s7, s8
	s_ashr_i32 s9, s7, 2
	s_ashr_i32 s8, s64, 31
	s_and_b32 s9, s9, -2
	s_lshr_b32 s8, s8, 24
	s_lshr_b32 s10, 32, s9
	s_and_b32 s6, s64, 31
	s_add_i32 s8, s64, s8
	s_lshr_b32 s11, 0x2000, s9
	s_sub_i32 s9, 5, s9
	s_add_i32 s10, s10, -1
	s_ashr_i32 s8, s8, 8
	s_lshr_b32 s9, s6, s9
	s_and_b32 s6, s10, s6
	s_lshl_b32 s10, s6, 8
	s_mul_i32 s6, s8, 24
	s_add_i32 s6, s6, s7
	s_mul_i32 s9, s9, s11
	s_ashr_i32 s7, s6, 31
	s_add_i32 s10, s10, s9
	v_add_u32_e32 v32, s10, v187
	s_lshl_b64 s[6:7], s[6:7], 20
	v_ashrrev_i32_e32 v33, 31, v32
	s_add_u32 s6, s40, s6
	s_addc_u32 s7, s41, s7
	v_lshlrev_b64 v[32:33], 7, v[32:33]
	v_lshl_add_u64 v[32:33], s[6:7], 0, v[32:33]
	v_lshl_add_u64 v[32:33], v[148:149], 1, v[32:33]
	global_load_dwordx4 v[96:99], v[32:33], off
	global_load_dwordx4 v[100:103], v[32:33], off offset:32
	global_load_dwordx4 v[104:107], v[32:33], off offset:64
	global_load_dwordx4 v[108:111], v[32:33], off offset:96
